# v13: v12 + loop-preheader vmcnt(0) in front of the out_proj / ffn_in / ffn_out K-loops removed (in-loop counted waits are at least as strict)
# baseline (speedup 1.0000x reference)
; #define PG8_STAGE(bufoff, gbase, voff) do { _Pragma("unroll") for (int _i = 0; _i < 2; ++_i) \
;         __builtin_amdgcn_global_load_lds((const unsigned*)((const char*)(gbase) + (voff)[_i]), (PG8_LAS unsigned*)(lds + (bufoff) + ldsw + _i * 8192), 16, 0, 0); } while (0)
; #define PG8_LDA(dst, b, h) do { _Pragma("unroll") for (int m = 0; m < 4; ++m) _Pragma("unroll") for (int k = 0; k < 2; ++k) dst[m][k] = *(const PG8_LAS bf16x8*)(lds + PG8_SA(b, h) + aoff + m * 2048 + k * 1024); } while (0)
; #define PG8_LDB(dst, b, h) do { _Pragma("unroll") for (int n = 0; n < 2; ++n) _Pragma("unroll") for (int k = 0; k < 2; ++k) dst[n][k] = *(const PG8_LAS bf16x8*)(lds + PG8_SB(b, h) + boff + n * 2048 + k * 1024); } while (0)
; #define PG8_WAIT_V(n) asm volatile("s_waitcnt vmcnt(" #n ")" ::: "memory")
; template <class Epi, class Sched, bool ALIGN_EPI = false, bool SP2 = false, bool I8 = false, bool F16 = false>
; __device__ __forceinline__ void gemm_phase(PG8_LAS unsigned char* lds, const Gemm g, const Sched& S, const Epi& E) {
;     ...
;     for (;;) {
;         const bool has_next = S.next(ui + 1, nxt);
;         const char* nA = has_next ? (const char*)g.A + (size_t)nxt.pm * tstep : cA; const char* nB = has_next ? (const char*)g.Bt + (size_t)nxt.pn * tstep : cB;
;         for (int t = 0; t < nt; t += 2) {
;             const bool last = (t == nt - 2);
;             const char* a1 = cA + (size_t)(t + 1) * kstep;
;             const char* a2 = last ? nA : cA + (size_t)(t + 2) * kstep; const char* b2 = last ? nB : cB + (size_t)(t + 2) * kstep;
;             const char* a3 = a2 + kstep; const char* b3 = b2 + kstep;
;             if (last && has_next) S.a_ready(nxt);
;             if constexpr (SP2) {
;             PG8_LDB(B0, 0, 0); PG8_LDB(B1, 0, 1); PG8_SCHED; PG8_LDA(At, 0, 0); PG8_STAGE(PG8_SA(1, 1), a1 + hstep, voffA);
;             PG8_WAIT_V(8); PG8_WAIT_L(0); PG8_BAR; PG8_MMA(0, 0, At, B0); PG8_MMA(0, 1, At, B1); PG8_BAR; PG8_SCHED;
;             PG8_LDA(At, 0, 1); PG8_STAGE(PG8_SB(0, 0), b2, voffB); PG8_STAGE(PG8_SB(0, 1), b2 + hstep, voffB); PG8_STAGE(PG8_SA(0, 0), a2, voffA);
;     ...
; #pragma unroll
;         for (int a = 0; a < 2; ++a)
; #pragma unroll
;             for (int b = 0; b < 2; ++b)
; #pragma unroll
;                 for (int m = 0; m < 4; ++m)
; #pragma unroll
;                     for (int n = 0; n < 2; ++n) acc[a][b][m][n] = (accv_t){0, 0, 0, 0};
.LBB0_915:
	s_ashr_i32 s43, s42, 31
	s_lshl_b64 s[30:31], s[42:43], 21
	s_add_u32 s44, s26, s30
	s_addc_u32 s45, s27, s31
	s_and_b64 s[30:31], s[6:7], exec
	s_cselect_b32 s43, s45, s51
	s_cselect_b32 s70, s44, s50
	s_ashr_i32 s37, s36, 31
	s_lshl_b64 s[30:31], s[36:37], 21
	s_add_u32 s46, s28, s30
	s_addc_u32 s47, s29, s31
	s_and_b64 s[30:31], s[6:7], exec
	s_cselect_b32 s37, s47, s53
	s_cselect_b32 s71, s46, s52
	s_add_u32 s50, s50, 0x100080
	s_addc_u32 s51, s51, 0
	s_add_u32 s79, s52, 0x100
	v_mov_b32_e32 v2, 0
	s_addc_u32 s81, s53, 0
	s_mov_b32 s83, -2
	v_mov_b32_e32 v3, v2
	v_mov_b32_e32 v4, v2
	v_mov_b32_e32 v5, v2
	v_mov_b32_e32 v6, v2
	v_mov_b32_e32 v7, v2
	v_mov_b32_e32 v8, v2
	v_mov_b32_e32 v9, v2
	v_mov_b32_e32 v14, v2
	v_mov_b32_e32 v15, v2
	v_mov_b32_e32 v16, v2
	v_mov_b32_e32 v17, v2
	v_mov_b32_e32 v22, v2
	v_mov_b32_e32 v23, v2
	v_mov_b32_e32 v24, v2
	v_mov_b32_e32 v25, v2
	v_mov_b32_e32 v30, v2
	v_mov_b32_e32 v31, v2
	v_mov_b32_e32 v32, v2
	v_mov_b32_e32 v33, v2
	v_mov_b32_e32 v38, v2
	v_mov_b32_e32 v39, v2
	v_mov_b32_e32 v40, v2
	v_mov_b32_e32 v41, v2
	v_mov_b32_e32 v46, v2
	v_mov_b32_e32 v47, v2
	v_mov_b32_e32 v48, v2
	v_mov_b32_e32 v49, v2
	v_mov_b32_e32 v54, v2
	v_mov_b32_e32 v55, v2
	v_mov_b32_e32 v56, v2
	v_mov_b32_e32 v57, v2
	v_mov_b32_e32 v10, v2
	v_mov_b32_e32 v11, v2
	v_mov_b32_e32 v12, v2
	v_mov_b32_e32 v13, v2
	v_mov_b32_e32 v18, v2
	v_mov_b32_e32 v19, v2
	v_mov_b32_e32 v20, v2
	v_mov_b32_e32 v21, v2
	v_mov_b32_e32 v26, v2
	v_mov_b32_e32 v27, v2
	v_mov_b32_e32 v28, v2
	v_mov_b32_e32 v29, v2
	v_mov_b32_e32 v34, v2
	v_mov_b32_e32 v35, v2
	v_mov_b32_e32 v36, v2
	v_mov_b32_e32 v37, v2
	v_mov_b32_e32 v42, v2
	v_mov_b32_e32 v43, v2
	v_mov_b32_e32 v44, v2
	v_mov_b32_e32 v45, v2
	v_mov_b32_e32 v50, v2
	v_mov_b32_e32 v51, v2
	v_mov_b32_e32 v52, v2
	v_mov_b32_e32 v53, v2
	v_mov_b32_e32 v58, v2
	v_mov_b32_e32 v59, v2
	v_mov_b32_e32 v60, v2
	v_mov_b32_e32 v61, v2
	v_mov_b32_e32 v62, v2
	v_mov_b32_e32 v63, v2
	v_mov_b32_e32 v64, v2
	v_mov_b32_e32 v65, v2
	v_mov_b32_e32 v66, v2
	v_mov_b32_e32 v67, v2
	v_mov_b32_e32 v68, v2
	v_mov_b32_e32 v69, v2
	v_mov_b32_e32 v70, v2
	v_mov_b32_e32 v71, v2
	v_mov_b32_e32 v72, v2
	v_mov_b32_e32 v73, v2
	v_mov_b32_e32 v78, v2
	v_mov_b32_e32 v79, v2
	v_mov_b32_e32 v80, v2
	v_mov_b32_e32 v81, v2
	v_mov_b32_e32 v86, v2
	v_mov_b32_e32 v87, v2
	v_mov_b32_e32 v88, v2
	v_mov_b32_e32 v89, v2
	v_mov_b32_e32 v94, v2
	v_mov_b32_e32 v95, v2
	v_mov_b32_e32 v96, v2
	v_mov_b32_e32 v97, v2
	v_mov_b32_e32 v102, v2
	v_mov_b32_e32 v103, v2
	v_mov_b32_e32 v104, v2
	v_mov_b32_e32 v105, v2
	v_mov_b32_e32 v114, v2
	v_mov_b32_e32 v115, v2
	v_mov_b32_e32 v116, v2
	v_mov_b32_e32 v117, v2
	v_mov_b32_e32 v118, v2
	v_mov_b32_e32 v119, v2
	v_mov_b32_e32 v120, v2
	v_mov_b32_e32 v121, v2
	v_mov_b32_e32 v74, v2
	v_mov_b32_e32 v75, v2
	v_mov_b32_e32 v76, v2
	v_mov_b32_e32 v77, v2
	v_mov_b32_e32 v82, v2
	v_mov_b32_e32 v83, v2
	v_mov_b32_e32 v84, v2
	v_mov_b32_e32 v85, v2
	v_mov_b32_e32 v90, v2
	v_mov_b32_e32 v91, v2
	v_mov_b32_e32 v92, v2
	v_mov_b32_e32 v93, v2
	v_mov_b32_e32 v98, v2
	v_mov_b32_e32 v99, v2
	v_mov_b32_e32 v100, v2
	v_mov_b32_e32 v101, v2
	v_mov_b32_e32 v106, v2
	v_mov_b32_e32 v107, v2
	v_mov_b32_e32 v108, v2
	v_mov_b32_e32 v109, v2
	v_mov_b32_e32 v110, v2
	v_mov_b32_e32 v111, v2
	v_mov_b32_e32 v112, v2
	v_mov_b32_e32 v113, v2
	v_mov_b32_e32 v122, v2
	v_mov_b32_e32 v123, v2
	v_mov_b32_e32 v124, v2
	v_mov_b32_e32 v125, v2
	v_mov_b32_e32 v126, v2
	v_mov_b32_e32 v127, v2
	v_mov_b32_e32 v128, v2
	v_mov_b32_e32 v129, v2
.LBB0_916:
	s_add_u32 s30, s50, 0xfff00080
	s_addc_u32 s31, s51, -1
	s_add_i32 s85, 0, 0x10000
	s_cmp_eq_u32 s83, 60
	s_cselect_b32 s55, s43, s31
	s_cselect_b32 s54, s70, s30
	s_cselect_b32 s53, s37, s81
	s_cselect_b32 s52, s71, s79
	s_add_i32 vcc_lo, 0, 0x14000
	v_add_u32_e32 v142, s85, v176
	v_add_u32_e32 v168, vcc_lo, v176
	ds_read_b128 v[130:133], v142
	ds_read_b128 v[134:137], v142 offset:1024
	ds_read_b128 v[138:141], v142 offset:2048
	ds_read_b128 v[142:145], v142 offset:3072
	ds_read_b128 v[146:149], v168
	ds_read_b128 v[150:153], v168 offset:1024
	ds_read_b128 v[164:167], v168 offset:2048
	ds_read_b128 v[168:171], v168 offset:3072
	v_lshl_add_u64 v[180:181], s[50:51], 0, v[160:161]
	s_add_i32 m0, s57, 0xc000
	ds_read_b128 v[172:175], v178
	ds_read_b128 v[198:201], v178 offset:1024
	ds_read_b128 v[202:205], v178 offset:2048
	ds_read_b128 v[206:209], v178 offset:3072
	ds_read_b128 v[226:229], v178 offset:4096
	ds_read_b128 v[230:233], v178 offset:5120
	ds_read_b128 v[234:237], v178 offset:6144
	ds_read_b128 v[238:241], v178 offset:7168
	global_load_lds_dwordx4 v[180:181], off
	v_lshl_add_u64 v[180:181], s[50:51], 0, v[162:163]
	s_add_i32 m0, s57, 0xe000
	s_nop 0
	global_load_lds_dwordx4 v[180:181], off
	s_waitcnt vmcnt(8)
	s_waitcnt lgkmcnt(0)
	s_setprio 1
	s_barrier
; #define PG8_STAGE(bufoff, gbase, voff) do { _Pragma("unroll") for (int _i = 0; _i < 2; ++_i) \
;         __builtin_amdgcn_global_load_lds((const unsigned*)((const char*)(gbase) + (voff)[_i]), (PG8_LAS unsigned*)(lds + (bufoff) + ldsw + _i * 8192), 16, 0, 0); } while (0)
; #define PG8_LDA(dst, b, h) do { _Pragma("unroll") for (int m = 0; m < 4; ++m) _Pragma("unroll") for (int k = 0; k < 2; ++k) dst[m][k] = *(const PG8_LAS bf16x8*)(lds + PG8_SA(b, h) + aoff + m * 2048 + k * 1024); } while (0)
; #define PG8_WAIT_V(n) asm volatile("s_waitcnt vmcnt(" #n ")" ::: "memory")
; #define PG8_WAIT_L(n) asm volatile("s_waitcnt lgkmcnt(" #n ")" ::: "memory")
; #define PG8_BAR __builtin_amdgcn_s_barrier()
; #define PG8_SCHED __builtin_amdgcn_sched_barrier(0)
; template <class Epi, class Sched, bool ALIGN_EPI = false, bool SP2 = false, bool I8 = false, bool F16 = false>
; __device__ __forceinline__ void gemm_phase(PG8_LAS unsigned char* lds, const Gemm g, const Sched& S, const Epi& E) {
;     ...
;             PG8_WAIT_V(8); PG8_WAIT_L(0); PG8_BAR; PG8_MMA(0, 0, At, B0); PG8_MMA(0, 1, At, B1); PG8_BAR; PG8_SCHED;
;             PG8_LDA(At, 0, 1); PG8_STAGE(PG8_SB(0, 0), b2, voffB); PG8_STAGE(PG8_SB(0, 1), b2 + hstep, voffB); PG8_STAGE(PG8_SA(0, 0), a2, voffA);
;             PG8_WAIT_V(8); PG8_WAIT_L(0); PG8_BAR; PG8_MMA(1, 0, At, B0); PG8_MMA(1, 1, At, B1); PG8_BAR; PG8_SCHED;
	v_mfma_f32_16x16x32_bf16 v[126:129], v[130:133], v[172:175], v[126:129]
	v_mfma_f32_16x16x32_bf16 v[122:125], v[138:141], v[172:175], v[122:125]
	v_mfma_f32_16x16x32_bf16 v[110:113], v[130:133], v[202:205], v[110:113]
	v_mfma_f32_16x16x32_bf16 v[106:109], v[138:141], v[202:205], v[106:109]
	v_mfma_f32_16x16x32_bf16 v[98:101], v[130:133], v[226:229], v[98:101]
	v_mfma_f32_16x16x32_bf16 v[90:93], v[138:141], v[226:229], v[90:93]
	v_mfma_f32_16x16x32_bf16 v[82:85], v[130:133], v[234:237], v[82:85]
	v_mfma_f32_16x16x32_bf16 v[74:77], v[138:141], v[234:237], v[74:77]
	v_mfma_f32_16x16x32_bf16 v[126:129], v[134:137], v[198:201], v[126:129]
	v_mfma_f32_16x16x32_bf16 v[122:125], v[142:145], v[198:201], v[122:125]
	v_mfma_f32_16x16x32_bf16 v[110:113], v[134:137], v[206:209], v[110:113]
	v_mfma_f32_16x16x32_bf16 v[106:109], v[142:145], v[206:209], v[106:109]
	v_mfma_f32_16x16x32_bf16 v[98:101], v[134:137], v[230:233], v[98:101]
	v_mfma_f32_16x16x32_bf16 v[90:93], v[142:145], v[230:233], v[90:93]
	v_mfma_f32_16x16x32_bf16 v[82:85], v[134:137], v[238:241], v[82:85]
	v_mfma_f32_16x16x32_bf16 v[74:77], v[142:145], v[238:241], v[74:77]
	v_mfma_f32_16x16x32_bf16 v[118:121], v[146:149], v[172:175], v[118:121]
	v_mfma_f32_16x16x32_bf16 v[114:117], v[164:167], v[172:175], v[114:117]
	v_mfma_f32_16x16x32_bf16 v[102:105], v[146:149], v[202:205], v[102:105]
	v_mfma_f32_16x16x32_bf16 v[94:97], v[164:167], v[202:205], v[94:97]
	v_mfma_f32_16x16x32_bf16 v[86:89], v[146:149], v[226:229], v[86:89]
	v_mfma_f32_16x16x32_bf16 v[78:81], v[164:167], v[226:229], v[78:81]
	v_mfma_f32_16x16x32_bf16 v[70:73], v[146:149], v[234:237], v[70:73]
	v_mfma_f32_16x16x32_bf16 v[66:69], v[164:167], v[234:237], v[66:69]
	v_mfma_f32_16x16x32_bf16 v[118:121], v[150:153], v[198:201], v[118:121]
	v_mfma_f32_16x16x32_bf16 v[114:117], v[168:171], v[198:201], v[114:117]
	v_mfma_f32_16x16x32_bf16 v[102:105], v[150:153], v[206:209], v[102:105]
	v_mfma_f32_16x16x32_bf16 v[94:97], v[168:171], v[206:209], v[94:97]
	v_mfma_f32_16x16x32_bf16 v[86:89], v[150:153], v[230:233], v[86:89]
	v_mfma_f32_16x16x32_bf16 v[78:81], v[168:171], v[230:233], v[78:81]
	v_mfma_f32_16x16x32_bf16 v[70:73], v[150:153], v[238:241], v[70:73]
	v_mfma_f32_16x16x32_bf16 v[66:69], v[168:171], v[238:241], v[66:69]
	s_barrier
	s_setprio 0
	s_add_i32 s30, s85, s56
	v_lshl_add_u64 v[180:181], s[52:53], 0, v[182:183]
	s_mov_b32 m0, s30
	ds_read_b128 v[172:175], v178 offset:16384
	ds_read_b128 v[198:201], v178 offset:17408
	ds_read_b128 v[202:205], v178 offset:18432
	ds_read_b128 v[206:209], v178 offset:19456
	ds_read_b128 v[226:229], v178 offset:20480
	ds_read_b128 v[230:233], v178 offset:21504
	ds_read_b128 v[234:237], v178 offset:22528
	ds_read_b128 v[238:241], v178 offset:23552
	global_load_lds_dwordx4 v[180:181], off
	s_add_i32 m0, s30, 0x2000
	s_add_u32 s30, s52, 0x100000
	v_lshl_add_u64 v[210:211], s[52:53], 0, v[154:155]
	s_addc_u32 s31, s53, 0
	s_add_i32 s85, vcc_lo, s56
	global_load_lds_dwordx4 v[210:211], off
	v_lshl_add_u64 v[242:243], s[30:31], 0, v[182:183]
	s_mov_b32 m0, s85
	v_lshl_add_u64 v[244:245], s[54:55], 0, v[156:157]
	global_load_lds_dwordx4 v[242:243], off
	v_lshl_add_u64 v[242:243], s[30:31], 0, v[154:155]
	s_add_i32 m0, s85, 0x2000
	s_nop 0
	global_load_lds_dwordx4 v[242:243], off
	v_lshl_add_u64 v[242:243], s[54:55], 0, v[158:159]
	s_mov_b32 m0, s57
	s_nop 0
	global_load_lds_dwordx4 v[242:243], off
	s_mov_b32 m0, s58
	s_nop 0
	global_load_lds_dwordx4 v[244:245], off
	s_waitcnt vmcnt(8)
	s_waitcnt lgkmcnt(0)
	s_setprio 1
	s_barrier
	v_mfma_f32_16x16x32_bf16 v[62:65], v[130:133], v[172:175], v[62:65]
	v_mfma_f32_16x16x32_bf16 v[58:61], v[138:141], v[172:175], v[58:61]
	v_mfma_f32_16x16x32_bf16 v[50:53], v[130:133], v[202:205], v[50:53]
	v_mfma_f32_16x16x32_bf16 v[42:45], v[138:141], v[202:205], v[42:45]
	v_mfma_f32_16x16x32_bf16 v[34:37], v[130:133], v[226:229], v[34:37]
	v_mfma_f32_16x16x32_bf16 v[26:29], v[138:141], v[226:229], v[26:29]
	v_mfma_f32_16x16x32_bf16 v[18:21], v[130:133], v[234:237], v[18:21]
	v_mfma_f32_16x16x32_bf16 v[10:13], v[138:141], v[234:237], v[10:13]
	v_mfma_f32_16x16x32_bf16 v[62:65], v[134:137], v[198:201], v[62:65]
	v_mfma_f32_16x16x32_bf16 v[58:61], v[142:145], v[198:201], v[58:61]
	v_mfma_f32_16x16x32_bf16 v[50:53], v[134:137], v[206:209], v[50:53]
	v_mfma_f32_16x16x32_bf16 v[42:45], v[142:145], v[206:209], v[42:45]
	v_mfma_f32_16x16x32_bf16 v[34:37], v[134:137], v[230:233], v[34:37]
	v_mfma_f32_16x16x32_bf16 v[26:29], v[142:145], v[230:233], v[26:29]
	v_mfma_f32_16x16x32_bf16 v[18:21], v[134:137], v[238:241], v[18:21]
	v_mfma_f32_16x16x32_bf16 v[10:13], v[142:145], v[238:241], v[10:13]
	v_mfma_f32_16x16x32_bf16 v[54:57], v[146:149], v[172:175], v[54:57]
	v_mfma_f32_16x16x32_bf16 v[46:49], v[164:167], v[172:175], v[46:49]
	v_mfma_f32_16x16x32_bf16 v[38:41], v[146:149], v[202:205], v[38:41]
	v_mfma_f32_16x16x32_bf16 v[30:33], v[164:167], v[202:205], v[30:33]
	v_mfma_f32_16x16x32_bf16 v[22:25], v[146:149], v[226:229], v[22:25]
	v_mfma_f32_16x16x32_bf16 v[14:17], v[164:167], v[226:229], v[14:17]
	v_mfma_f32_16x16x32_bf16 v[6:9], v[146:149], v[234:237], v[6:9]
	v_mfma_f32_16x16x32_bf16 v[2:5], v[164:167], v[234:237], v[2:5]
	v_mfma_f32_16x16x32_bf16 v[54:57], v[150:153], v[198:201], v[54:57]
	v_mfma_f32_16x16x32_bf16 v[46:49], v[168:171], v[198:201], v[46:49]
	v_mfma_f32_16x16x32_bf16 v[38:41], v[150:153], v[206:209], v[38:41]
	v_mfma_f32_16x16x32_bf16 v[30:33], v[168:171], v[206:209], v[30:33]
	v_mfma_f32_16x16x32_bf16 v[22:25], v[150:153], v[230:233], v[22:25]
	v_mfma_f32_16x16x32_bf16 v[14:17], v[168:171], v[230:233], v[14:17]
	v_mfma_f32_16x16x32_bf16 v[6:9], v[150:153], v[238:241], v[6:9]
	v_mfma_f32_16x16x32_bf16 v[2:5], v[168:171], v[238:241], v[2:5]
	s_barrier
; #define PG8_STAGE(bufoff, gbase, voff) do { _Pragma("unroll") for (int _i = 0; _i < 2; ++_i) \
;         __builtin_amdgcn_global_load_lds((const unsigned*)((const char*)(gbase) + (voff)[_i]), (PG8_LAS unsigned*)(lds + (bufoff) + ldsw + _i * 8192), 16, 0, 0); } while (0)
; #define PG8_LDA(dst, b, h) do { _Pragma("unroll") for (int m = 0; m < 4; ++m) _Pragma("unroll") for (int k = 0; k < 2; ++k) dst[m][k] = *(const PG8_LAS bf16x8*)(lds + PG8_SA(b, h) + aoff + m * 2048 + k * 1024); } while (0)
; #define PG8_LDB(dst, b, h) do { _Pragma("unroll") for (int n = 0; n < 2; ++n) _Pragma("unroll") for (int k = 0; k < 2; ++k) dst[n][k] = *(const PG8_LAS bf16x8*)(lds + PG8_SB(b, h) + boff + n * 2048 + k * 1024); } while (0)
; #define PG8_WAIT_V(n) asm volatile("s_waitcnt vmcnt(" #n ")" ::: "memory")
; #define PG8_WAIT_L(n) asm volatile("s_waitcnt lgkmcnt(" #n ")" ::: "memory")
; #define PG8_BAR __builtin_amdgcn_s_barrier()
; #define PG8_SCHED __builtin_amdgcn_sched_barrier(0)
; template <class Epi, class Sched, bool ALIGN_EPI = false, bool SP2 = false, bool I8 = false, bool F16 = false>
; __device__ __forceinline__ void gemm_phase(PG8_LAS unsigned char* lds, const Gemm g, const Sched& S, const Epi& E) {
;     ...
;             PG8_LDB(B0, 1, 0); PG8_LDB(B1, 1, 1); PG8_SCHED; PG8_LDA(At, 1, 0); PG8_STAGE(PG8_SA(0, 1), a2 + hstep, voffA);
;             PG8_WAIT_V(8); PG8_WAIT_L(0); PG8_BAR; PG8_MMA(0, 0, At, B0); PG8_MMA(0, 1, At, B1); PG8_BAR; PG8_SCHED;
	s_setprio 0
	s_add_i32 s85, 0, 0x18000
	s_add_i32 vcc_lo, 0, 0x1c000
	v_add_u32_e32 v142, s85, v176
	v_add_u32_e32 v168, vcc_lo, v176
	ds_read_b128 v[130:133], v142
	ds_read_b128 v[134:137], v142 offset:1024
	ds_read_b128 v[138:141], v142 offset:2048
	ds_read_b128 v[142:145], v142 offset:3072
	ds_read_b128 v[146:149], v168
	ds_read_b128 v[150:153], v168 offset:1024
	ds_read_b128 v[164:167], v168 offset:2048
	ds_read_b128 v[168:171], v168 offset:3072
	s_add_u32 s30, s54, 0x100000
	s_addc_u32 s31, s55, 0
	s_mov_b32 m0, s59
	v_lshl_add_u64 v[246:247], s[30:31], 0, v[158:159]
	ds_read_b128 v[172:175], v178 offset:32768
	ds_read_b128 v[198:201], v178 offset:33792
	ds_read_b128 v[202:205], v178 offset:34816
	ds_read_b128 v[206:209], v178 offset:35840
	ds_read_b128 v[226:229], v178 offset:36864
	ds_read_b128 v[230:233], v178 offset:37888
	ds_read_b128 v[234:237], v178 offset:38912
	ds_read_b128 v[238:241], v178 offset:39936
	global_load_lds_dwordx4 v[246:247], off
	v_lshl_add_u64 v[246:247], s[30:31], 0, v[156:157]
	s_mov_b32 m0, s62
	s_nop 0
	global_load_lds_dwordx4 v[246:247], off
	s_waitcnt vmcnt(8)
	s_waitcnt lgkmcnt(0)
	s_setprio 1
	s_barrier
	v_mfma_f32_16x16x32_bf16 v[126:129], v[130:133], v[172:175], v[126:129]
	v_mfma_f32_16x16x32_bf16 v[122:125], v[138:141], v[172:175], v[122:125]
	v_mfma_f32_16x16x32_bf16 v[110:113], v[130:133], v[202:205], v[110:113]
	v_mfma_f32_16x16x32_bf16 v[106:109], v[138:141], v[202:205], v[106:109]
	v_mfma_f32_16x16x32_bf16 v[98:101], v[130:133], v[226:229], v[98:101]
	v_mfma_f32_16x16x32_bf16 v[90:93], v[138:141], v[226:229], v[90:93]
	v_mfma_f32_16x16x32_bf16 v[82:85], v[130:133], v[234:237], v[82:85]
	v_mfma_f32_16x16x32_bf16 v[74:77], v[138:141], v[234:237], v[74:77]
	v_mfma_f32_16x16x32_bf16 v[126:129], v[134:137], v[198:201], v[126:129]
	v_mfma_f32_16x16x32_bf16 v[122:125], v[142:145], v[198:201], v[122:125]
	v_mfma_f32_16x16x32_bf16 v[110:113], v[134:137], v[206:209], v[110:113]
	v_mfma_f32_16x16x32_bf16 v[106:109], v[142:145], v[206:209], v[106:109]
	v_mfma_f32_16x16x32_bf16 v[98:101], v[134:137], v[230:233], v[98:101]
	v_mfma_f32_16x16x32_bf16 v[90:93], v[142:145], v[230:233], v[90:93]
	v_mfma_f32_16x16x32_bf16 v[82:85], v[134:137], v[238:241], v[82:85]
	v_mfma_f32_16x16x32_bf16 v[74:77], v[142:145], v[238:241], v[74:77]
	v_mfma_f32_16x16x32_bf16 v[118:121], v[146:149], v[172:175], v[118:121]
	v_mfma_f32_16x16x32_bf16 v[114:117], v[164:167], v[172:175], v[114:117]
	v_mfma_f32_16x16x32_bf16 v[102:105], v[146:149], v[202:205], v[102:105]
	v_mfma_f32_16x16x32_bf16 v[94:97], v[164:167], v[202:205], v[94:97]
	v_mfma_f32_16x16x32_bf16 v[86:89], v[146:149], v[226:229], v[86:89]
	v_mfma_f32_16x16x32_bf16 v[78:81], v[164:167], v[226:229], v[78:81]
	v_mfma_f32_16x16x32_bf16 v[70:73], v[146:149], v[234:237], v[70:73]
	v_mfma_f32_16x16x32_bf16 v[66:69], v[164:167], v[234:237], v[66:69]
	v_mfma_f32_16x16x32_bf16 v[118:121], v[150:153], v[198:201], v[118:121]
	v_mfma_f32_16x16x32_bf16 v[114:117], v[168:171], v[198:201], v[114:117]
	v_mfma_f32_16x16x32_bf16 v[102:105], v[150:153], v[206:209], v[102:105]
	v_mfma_f32_16x16x32_bf16 v[94:97], v[168:171], v[206:209], v[94:97]
	v_mfma_f32_16x16x32_bf16 v[86:89], v[150:153], v[230:233], v[86:89]
	v_mfma_f32_16x16x32_bf16 v[78:81], v[168:171], v[230:233], v[78:81]
	v_mfma_f32_16x16x32_bf16 v[70:73], v[150:153], v[238:241], v[70:73]
	v_mfma_f32_16x16x32_bf16 v[66:69], v[168:171], v[238:241], v[66:69]
	s_barrier
; #define PG8_STAGE(bufoff, gbase, voff) do { _Pragma("unroll") for (int _i = 0; _i < 2; ++_i) \
;         __builtin_amdgcn_global_load_lds((const unsigned*)((const char*)(gbase) + (voff)[_i]), (PG8_LAS unsigned*)(lds + (bufoff) + ldsw + _i * 8192), 16, 0, 0); } while (0)
; #define PG8_LDA(dst, b, h) do { _Pragma("unroll") for (int m = 0; m < 4; ++m) _Pragma("unroll") for (int k = 0; k < 2; ++k) dst[m][k] = *(const PG8_LAS bf16x8*)(lds + PG8_SA(b, h) + aoff + m * 2048 + k * 1024); } while (0)
; #define PG8_WAIT_V(n) asm volatile("s_waitcnt vmcnt(" #n ")" ::: "memory")
; #define PG8_WAIT_L(n) asm volatile("s_waitcnt lgkmcnt(" #n ")" ::: "memory")
; #define PG8_BAR __builtin_amdgcn_s_barrier()
; #define PG8_SCHED __builtin_amdgcn_sched_barrier(0)
; template <class Epi, class Sched, bool ALIGN_EPI = false, bool SP2 = false, bool I8 = false, bool F16 = false>
; __device__ __forceinline__ void gemm_phase(PG8_LAS unsigned char* lds, const Gemm g, const Sched& S, const Epi& E) {
;     ...
;             PG8_LDA(At, 1, 1); PG8_STAGE(PG8_SB(1, 0), b3, voffB); PG8_STAGE(PG8_SB(1, 1), b3 + hstep, voffB); PG8_STAGE(PG8_SA(1, 0), a3, voffA);
;             PG8_WAIT_V(8); PG8_WAIT_L(0); PG8_BAR; PG8_MMA(1, 0, At, B0); PG8_MMA(1, 1, At, B1); PG8_BAR; PG8_SCHED;
;     ...
;         if constexpr (ALIGN_EPI) { if (wr == 0) PG8_BAR; }
	s_setprio 0
	s_add_i32 s30, s85, s56
	v_lshl_add_u64 v[180:181], v[180:181], 0, s[74:75]
	s_mov_b32 m0, s30
	ds_read_b128 v[172:175], v178 offset:49152
	ds_read_b128 v[198:201], v178 offset:50176
	ds_read_b128 v[202:205], v178 offset:51200
	ds_read_b128 v[206:209], v178 offset:52224
	ds_read_b128 v[226:229], v178 offset:53248
	ds_read_b128 v[230:233], v178 offset:54272
	ds_read_b128 v[234:237], v178 offset:55296
	ds_read_b128 v[238:241], v178 offset:56320
	global_load_lds_dwordx4 v[180:181], off
	s_add_i32 m0, s30, 0x2000
	s_add_u32 s30, s52, 0x100080
	v_lshl_add_u64 v[180:181], v[210:211], 0, s[74:75]
	s_addc_u32 s31, s53, 0
	s_add_i32 s52, vcc_lo, s56
	global_load_lds_dwordx4 v[180:181], off
	v_lshl_add_u64 v[180:181], s[30:31], 0, v[182:183]
	s_mov_b32 m0, s52
	s_nop 0
	global_load_lds_dwordx4 v[180:181], off
	v_lshl_add_u64 v[180:181], s[30:31], 0, v[154:155]
	s_add_i32 m0, s52, 0x2000
	s_nop 0
	global_load_lds_dwordx4 v[180:181], off
	v_lshl_add_u64 v[180:181], v[242:243], 0, s[74:75]
	s_mov_b32 m0, s64
	s_nop 0
	global_load_lds_dwordx4 v[180:181], off
	v_lshl_add_u64 v[180:181], v[244:245], 0, s[74:75]
	s_mov_b32 m0, s65
	s_nop 0
	global_load_lds_dwordx4 v[180:181], off
	s_waitcnt vmcnt(8)
	s_waitcnt lgkmcnt(0)
	s_setprio 1
	s_barrier
	v_mfma_f32_16x16x32_bf16 v[62:65], v[130:133], v[172:175], v[62:65]
	v_mfma_f32_16x16x32_bf16 v[58:61], v[138:141], v[172:175], v[58:61]
	v_mfma_f32_16x16x32_bf16 v[50:53], v[130:133], v[202:205], v[50:53]
	v_mfma_f32_16x16x32_bf16 v[42:45], v[138:141], v[202:205], v[42:45]
	v_mfma_f32_16x16x32_bf16 v[34:37], v[130:133], v[226:229], v[34:37]
	v_mfma_f32_16x16x32_bf16 v[26:29], v[138:141], v[226:229], v[26:29]
	v_mfma_f32_16x16x32_bf16 v[18:21], v[130:133], v[234:237], v[18:21]
	v_mfma_f32_16x16x32_bf16 v[10:13], v[138:141], v[234:237], v[10:13]
	v_mfma_f32_16x16x32_bf16 v[62:65], v[134:137], v[198:201], v[62:65]
	v_mfma_f32_16x16x32_bf16 v[58:61], v[142:145], v[198:201], v[58:61]
	v_mfma_f32_16x16x32_bf16 v[50:53], v[134:137], v[206:209], v[50:53]
	v_mfma_f32_16x16x32_bf16 v[42:45], v[142:145], v[206:209], v[42:45]
	v_mfma_f32_16x16x32_bf16 v[34:37], v[134:137], v[230:233], v[34:37]
	v_mfma_f32_16x16x32_bf16 v[26:29], v[142:145], v[230:233], v[26:29]
	v_mfma_f32_16x16x32_bf16 v[18:21], v[134:137], v[238:241], v[18:21]
	v_mfma_f32_16x16x32_bf16 v[10:13], v[142:145], v[238:241], v[10:13]
	v_mfma_f32_16x16x32_bf16 v[54:57], v[146:149], v[172:175], v[54:57]
	v_mfma_f32_16x16x32_bf16 v[46:49], v[164:167], v[172:175], v[46:49]
	v_mfma_f32_16x16x32_bf16 v[38:41], v[146:149], v[202:205], v[38:41]
	v_mfma_f32_16x16x32_bf16 v[30:33], v[164:167], v[202:205], v[30:33]
	v_mfma_f32_16x16x32_bf16 v[22:25], v[146:149], v[226:229], v[22:25]
	v_mfma_f32_16x16x32_bf16 v[14:17], v[164:167], v[226:229], v[14:17]
	v_mfma_f32_16x16x32_bf16 v[6:9], v[146:149], v[234:237], v[6:9]
	v_mfma_f32_16x16x32_bf16 v[2:5], v[164:167], v[234:237], v[2:5]
	v_mfma_f32_16x16x32_bf16 v[54:57], v[150:153], v[198:201], v[54:57]
	v_mfma_f32_16x16x32_bf16 v[46:49], v[168:171], v[198:201], v[46:49]
	v_mfma_f32_16x16x32_bf16 v[38:41], v[150:153], v[206:209], v[38:41]
	v_mfma_f32_16x16x32_bf16 v[30:33], v[168:171], v[206:209], v[30:33]
	v_mfma_f32_16x16x32_bf16 v[22:25], v[150:153], v[230:233], v[22:25]
	v_mfma_f32_16x16x32_bf16 v[14:17], v[168:171], v[230:233], v[14:17]
	v_mfma_f32_16x16x32_bf16 v[6:9], v[150:153], v[238:241], v[6:9]
	v_mfma_f32_16x16x32_bf16 v[2:5], v[168:171], v[238:241], v[2:5]
	s_barrier
	s_setprio 0
	s_add_i32 s83, s83, 2
	s_add_u32 s50, s50, 0x100
	s_addc_u32 s51, s51, 0
	s_add_u32 s79, s79, 0x100
	s_addc_u32 s81, s81, 0
	s_cmp_gt_u32 s83, 61
	s_cbranch_scc0 .LBB0_916
	s_and_b64 vcc, exec, s[16:17]
	s_cbranch_vccz .LBB0_919
	s_barrier

; #define PG8_STAGE(bufoff, gbase, voff) do { _Pragma("unroll") for (int _i = 0; _i < 2; ++_i) \
;         __builtin_amdgcn_global_load_lds((const unsigned*)((const char*)(gbase) + (voff)[_i]), (PG8_LAS unsigned*)(lds + (bufoff) + ldsw + _i * 8192), 16, 0, 0); } while (0)
; #define PG8_LDA(dst, b, h) do { _Pragma("unroll") for (int m = 0; m < 4; ++m) _Pragma("unroll") for (int k = 0; k < 2; ++k) dst[m][k] = *(const PG8_LAS bf16x8*)(lds + PG8_SA(b, h) + aoff + m * 2048 + k * 1024); } while (0)
; #define PG8_LDB(dst, b, h) do { _Pragma("unroll") for (int n = 0; n < 2; ++n) _Pragma("unroll") for (int k = 0; k < 2; ++k) dst[n][k] = *(const PG8_LAS bf16x8*)(lds + PG8_SB(b, h) + boff + n * 2048 + k * 1024); } while (0)
; #define PG8_WAIT_V(n) asm volatile("s_waitcnt vmcnt(" #n ")" ::: "memory")
; template <class Epi, class Sched, bool ALIGN_EPI = false, bool SP2 = false, bool I8 = false, bool F16 = false>
; __device__ __forceinline__ void gemm_phase(PG8_LAS unsigned char* lds, const Gemm g, const Sched& S, const Epi& E) {
;     ...
;     for (;;) {
;         const bool has_next = S.next(ui + 1, nxt);
;         const char* nA = has_next ? (const char*)g.A + (size_t)nxt.pm * tstep : cA; const char* nB = has_next ? (const char*)g.Bt + (size_t)nxt.pn * tstep : cB;
;         for (int t = 0; t < nt; t += 2) {
;             const bool last = (t == nt - 2);
;             const char* a1 = cA + (size_t)(t + 1) * kstep;
;             const char* a2 = last ? nA : cA + (size_t)(t + 2) * kstep; const char* b2 = last ? nB : cB + (size_t)(t + 2) * kstep;
;             const char* a3 = a2 + kstep; const char* b3 = b2 + kstep;
;             if (last && has_next) S.a_ready(nxt);
;             if constexpr (SP2) {
;             PG8_LDB(B0, 0, 0); PG8_LDB(B1, 0, 1); PG8_SCHED; PG8_LDA(At, 0, 0); PG8_STAGE(PG8_SA(1, 1), a1 + hstep, voffA);
;             PG8_WAIT_V(8); PG8_WAIT_L(0); PG8_BAR; PG8_MMA(0, 0, At, B0); PG8_MMA(0, 1, At, B1); PG8_BAR; PG8_SCHED;
;             PG8_LDA(At, 0, 1); PG8_STAGE(PG8_SB(0, 0), b2, voffB); PG8_STAGE(PG8_SB(0, 1), b2 + hstep, voffB); PG8_STAGE(PG8_SA(0, 0), a2, voffA);
;     ...
; #pragma unroll
;         for (int a = 0; a < 2; ++a)
; #pragma unroll
;             for (int b = 0; b < 2; ++b)
; #pragma unroll
;                 for (int m = 0; m < 4; ++m)
; #pragma unroll
;                     for (int n = 0; n < 2; ++n) acc[a][b][m][n] = (accv_t){0, 0, 0, 0};
.LBB0_1056:
	s_ashr_i32 s45, s44, 31
	s_lshl_b64 s[30:31], s[44:45], 20
	s_add_u32 s46, s26, s30
	s_addc_u32 s47, s27, s31
	s_and_b64 s[30:31], s[6:7], exec
	s_cselect_b32 s45, s47, s53
	s_cselect_b32 s79, s46, s52
	s_ashr_i32 s43, s42, 31
	s_lshl_b64 s[30:31], s[42:43], 20
	s_add_u32 s50, s28, s30
	s_addc_u32 s51, s29, s31
	s_and_b64 s[30:31], s[6:7], exec
	s_cselect_b32 s43, s51, s55
	s_cselect_b32 s81, s50, s54
	s_add_u32 s52, s52, 0x80080
	s_addc_u32 s53, s53, 0
	s_add_u32 s83, s54, 0x100
	v_mov_b32_e32 v2, 0
	s_addc_u32 s85, s55, 0
	s_mov_b32 vcc_lo, -2
	v_mov_b32_e32 v3, v2
	v_mov_b32_e32 v4, v2
	v_mov_b32_e32 v5, v2
	v_mov_b32_e32 v10, v2
	v_mov_b32_e32 v11, v2
	v_mov_b32_e32 v12, v2
	v_mov_b32_e32 v13, v2
	v_mov_b32_e32 v18, v2
	v_mov_b32_e32 v19, v2
	v_mov_b32_e32 v20, v2
	v_mov_b32_e32 v21, v2
	v_mov_b32_e32 v26, v2
	v_mov_b32_e32 v27, v2
	v_mov_b32_e32 v28, v2
	v_mov_b32_e32 v29, v2
	v_mov_b32_e32 v34, v2
	v_mov_b32_e32 v35, v2
	v_mov_b32_e32 v36, v2
	v_mov_b32_e32 v37, v2
	v_mov_b32_e32 v42, v2
	v_mov_b32_e32 v43, v2
	v_mov_b32_e32 v44, v2
	v_mov_b32_e32 v45, v2
	v_mov_b32_e32 v50, v2
	v_mov_b32_e32 v51, v2
	v_mov_b32_e32 v52, v2
	v_mov_b32_e32 v53, v2
	v_mov_b32_e32 v58, v2
	v_mov_b32_e32 v59, v2
	v_mov_b32_e32 v60, v2
	v_mov_b32_e32 v61, v2
	v_mov_b32_e32 v6, v2
	v_mov_b32_e32 v7, v2
	v_mov_b32_e32 v8, v2
	v_mov_b32_e32 v9, v2
	v_mov_b32_e32 v14, v2
	v_mov_b32_e32 v15, v2
	v_mov_b32_e32 v16, v2
	v_mov_b32_e32 v17, v2
	v_mov_b32_e32 v22, v2
	v_mov_b32_e32 v23, v2
	v_mov_b32_e32 v24, v2
	v_mov_b32_e32 v25, v2
	v_mov_b32_e32 v30, v2
	v_mov_b32_e32 v31, v2
	v_mov_b32_e32 v32, v2
	v_mov_b32_e32 v33, v2
	v_mov_b32_e32 v38, v2
	v_mov_b32_e32 v39, v2
	v_mov_b32_e32 v40, v2
	v_mov_b32_e32 v41, v2
	v_mov_b32_e32 v46, v2
	v_mov_b32_e32 v47, v2
	v_mov_b32_e32 v48, v2
	v_mov_b32_e32 v49, v2
	v_mov_b32_e32 v54, v2
	v_mov_b32_e32 v55, v2
	v_mov_b32_e32 v56, v2
	v_mov_b32_e32 v57, v2
	v_mov_b32_e32 v62, v2
	v_mov_b32_e32 v63, v2
	v_mov_b32_e32 v64, v2
	v_mov_b32_e32 v65, v2
	v_mov_b32_e32 v66, v2
	v_mov_b32_e32 v67, v2
	v_mov_b32_e32 v68, v2
	v_mov_b32_e32 v69, v2
	v_mov_b32_e32 v74, v2
	v_mov_b32_e32 v75, v2
	v_mov_b32_e32 v76, v2
	v_mov_b32_e32 v77, v2
	v_mov_b32_e32 v82, v2
	v_mov_b32_e32 v83, v2
	v_mov_b32_e32 v84, v2
	v_mov_b32_e32 v85, v2
	v_mov_b32_e32 v90, v2
	v_mov_b32_e32 v91, v2
	v_mov_b32_e32 v92, v2
	v_mov_b32_e32 v93, v2
	v_mov_b32_e32 v98, v2
	v_mov_b32_e32 v99, v2
	v_mov_b32_e32 v100, v2
	v_mov_b32_e32 v101, v2
	v_mov_b32_e32 v106, v2
	v_mov_b32_e32 v107, v2
	v_mov_b32_e32 v108, v2
	v_mov_b32_e32 v109, v2
	v_mov_b32_e32 v114, v2
	v_mov_b32_e32 v115, v2
	v_mov_b32_e32 v116, v2
	v_mov_b32_e32 v117, v2
	v_mov_b32_e32 v122, v2
	v_mov_b32_e32 v123, v2
	v_mov_b32_e32 v124, v2
	v_mov_b32_e32 v125, v2
	v_mov_b32_e32 v70, v2
	v_mov_b32_e32 v71, v2
	v_mov_b32_e32 v72, v2
	v_mov_b32_e32 v73, v2
	v_mov_b32_e32 v78, v2
	v_mov_b32_e32 v79, v2
	v_mov_b32_e32 v80, v2
	v_mov_b32_e32 v81, v2
	v_mov_b32_e32 v86, v2
	v_mov_b32_e32 v87, v2
	v_mov_b32_e32 v88, v2
	v_mov_b32_e32 v89, v2
	v_mov_b32_e32 v94, v2
	v_mov_b32_e32 v95, v2
	v_mov_b32_e32 v96, v2
	v_mov_b32_e32 v97, v2
	v_mov_b32_e32 v102, v2
	v_mov_b32_e32 v103, v2
	v_mov_b32_e32 v104, v2
	v_mov_b32_e32 v105, v2
	v_mov_b32_e32 v110, v2
	v_mov_b32_e32 v111, v2
	v_mov_b32_e32 v112, v2
	v_mov_b32_e32 v113, v2
	v_mov_b32_e32 v118, v2
	v_mov_b32_e32 v119, v2
	v_mov_b32_e32 v120, v2
	v_mov_b32_e32 v121, v2
	v_mov_b32_e32 v126, v2
	v_mov_b32_e32 v127, v2
	v_mov_b32_e32 v128, v2
	v_mov_b32_e32 v129, v2
.LBB0_1057:
	s_add_u32 s30, s52, 0xfff80080
	s_addc_u32 s31, s53, -1
	s_add_i32 vcc_hi, 0, 0x10000
	s_cmp_eq_u32 vcc_lo, 28
	s_cselect_b32 s57, s45, s31
	s_cselect_b32 s56, s79, s30
	v_add_u32_e32 v148, vcc_hi, v149
	s_cselect_b32 s55, s43, s85
	s_cselect_b32 s54, s81, s83
	s_add_i32 s4, 0, 0x14000
	ds_read_b128 v[140:143], v148
	ds_read_b128 v[144:147], v148 offset:1024
	ds_read_b128 v[154:157], v148 offset:2048
	ds_read_b128 v[158:161], v148 offset:3072
	v_add_u32_e32 v148, s4, v149
	ds_read_b128 v[162:165], v148
	ds_read_b128 v[166:169], v148 offset:1024
	ds_read_b128 v[170:173], v148 offset:2048
	ds_read_b128 v[174:177], v148 offset:3072
	v_lshl_add_u64 v[150:151], s[52:53], 0, v[136:137]
	s_add_i32 m0, s59, 0xc000
	ds_read_b128 v[178:181], v153
	ds_read_b128 v[198:201], v153 offset:1024
	ds_read_b128 v[202:205], v153 offset:2048
	ds_read_b128 v[206:209], v153 offset:3072
	ds_read_b128 v[226:229], v153 offset:4096
	ds_read_b128 v[230:233], v153 offset:5120
	ds_read_b128 v[234:237], v153 offset:6144
	ds_read_b128 v[238:241], v153 offset:7168
	global_load_lds_dwordx4 v[150:151], off
	v_lshl_add_u64 v[150:151], s[52:53], 0, v[138:139]
	s_add_i32 m0, s59, 0xe000
	s_nop 0
	global_load_lds_dwordx4 v[150:151], off
	s_waitcnt vmcnt(8)
	s_waitcnt lgkmcnt(0)
	s_setprio 1
	s_barrier
; #define PG8_STAGE(bufoff, gbase, voff) do { _Pragma("unroll") for (int _i = 0; _i < 2; ++_i) \
;         __builtin_amdgcn_global_load_lds((const unsigned*)((const char*)(gbase) + (voff)[_i]), (PG8_LAS unsigned*)(lds + (bufoff) + ldsw + _i * 8192), 16, 0, 0); } while (0)
; #define PG8_LDA(dst, b, h) do { _Pragma("unroll") for (int m = 0; m < 4; ++m) _Pragma("unroll") for (int k = 0; k < 2; ++k) dst[m][k] = *(const PG8_LAS bf16x8*)(lds + PG8_SA(b, h) + aoff + m * 2048 + k * 1024); } while (0)
; #define PG8_WAIT_V(n) asm volatile("s_waitcnt vmcnt(" #n ")" ::: "memory")
; #define PG8_WAIT_L(n) asm volatile("s_waitcnt lgkmcnt(" #n ")" ::: "memory")
; #define PG8_BAR __builtin_amdgcn_s_barrier()
; #define PG8_SCHED __builtin_amdgcn_sched_barrier(0)
; template <class Epi, class Sched, bool ALIGN_EPI = false, bool SP2 = false, bool I8 = false, bool F16 = false>
; __device__ __forceinline__ void gemm_phase(PG8_LAS unsigned char* lds, const Gemm g, const Sched& S, const Epi& E) {
;     ...
;             PG8_WAIT_V(8); PG8_WAIT_L(0); PG8_BAR; PG8_MMA(0, 0, At, B0); PG8_MMA(0, 1, At, B1); PG8_BAR; PG8_SCHED;
;             PG8_LDA(At, 0, 1); PG8_STAGE(PG8_SB(0, 0), b2, voffB); PG8_STAGE(PG8_SB(0, 1), b2 + hstep, voffB); PG8_STAGE(PG8_SA(0, 0), a2, voffA);
;             PG8_WAIT_V(8); PG8_WAIT_L(0); PG8_BAR; PG8_MMA(1, 0, At, B0); PG8_MMA(1, 1, At, B1); PG8_BAR; PG8_SCHED;
	v_mfma_i32_16x16x64_i8 v[126:129], v[140:143], v[178:181], v[126:129]
	v_mfma_i32_16x16x64_i8 v[118:121], v[154:157], v[178:181], v[118:121]
	v_mfma_i32_16x16x64_i8 v[110:113], v[140:143], v[202:205], v[110:113]
	v_mfma_i32_16x16x64_i8 v[102:105], v[154:157], v[202:205], v[102:105]
	v_mfma_i32_16x16x64_i8 v[94:97], v[140:143], v[226:229], v[94:97]
	v_mfma_i32_16x16x64_i8 v[86:89], v[154:157], v[226:229], v[86:89]
	v_mfma_i32_16x16x64_i8 v[78:81], v[140:143], v[234:237], v[78:81]
	v_mfma_i32_16x16x64_i8 v[70:73], v[154:157], v[234:237], v[70:73]
	v_mfma_i32_16x16x64_i8 v[126:129], v[144:147], v[198:201], v[126:129]
	v_mfma_i32_16x16x64_i8 v[118:121], v[158:161], v[198:201], v[118:121]
	v_mfma_i32_16x16x64_i8 v[110:113], v[144:147], v[206:209], v[110:113]
	v_mfma_i32_16x16x64_i8 v[102:105], v[158:161], v[206:209], v[102:105]
	v_mfma_i32_16x16x64_i8 v[94:97], v[144:147], v[230:233], v[94:97]
	v_mfma_i32_16x16x64_i8 v[86:89], v[158:161], v[230:233], v[86:89]
	v_mfma_i32_16x16x64_i8 v[78:81], v[144:147], v[238:241], v[78:81]
	v_mfma_i32_16x16x64_i8 v[70:73], v[158:161], v[238:241], v[70:73]
	v_mfma_i32_16x16x64_i8 v[122:125], v[162:165], v[178:181], v[122:125]
	v_mfma_i32_16x16x64_i8 v[114:117], v[170:173], v[178:181], v[114:117]
	v_mfma_i32_16x16x64_i8 v[106:109], v[162:165], v[202:205], v[106:109]
	v_mfma_i32_16x16x64_i8 v[98:101], v[170:173], v[202:205], v[98:101]
	v_mfma_i32_16x16x64_i8 v[90:93], v[162:165], v[226:229], v[90:93]
	v_mfma_i32_16x16x64_i8 v[82:85], v[170:173], v[226:229], v[82:85]
	v_mfma_i32_16x16x64_i8 v[74:77], v[162:165], v[234:237], v[74:77]
	v_mfma_i32_16x16x64_i8 v[66:69], v[170:173], v[234:237], v[66:69]
	v_mfma_i32_16x16x64_i8 v[122:125], v[166:169], v[198:201], v[122:125]
	v_mfma_i32_16x16x64_i8 v[114:117], v[174:177], v[198:201], v[114:117]
	v_mfma_i32_16x16x64_i8 v[106:109], v[166:169], v[206:209], v[106:109]
	v_mfma_i32_16x16x64_i8 v[98:101], v[174:177], v[206:209], v[98:101]
	v_mfma_i32_16x16x64_i8 v[90:93], v[166:169], v[230:233], v[90:93]
	v_mfma_i32_16x16x64_i8 v[82:85], v[174:177], v[230:233], v[82:85]
	v_mfma_i32_16x16x64_i8 v[74:77], v[166:169], v[238:241], v[74:77]
	v_mfma_i32_16x16x64_i8 v[66:69], v[174:177], v[238:241], v[66:69]
	s_barrier
	s_setprio 0
	s_add_i32 s5, vcc_hi, s58
	v_lshl_add_u64 v[150:151], s[54:55], 0, v[182:183]
	s_mov_b32 m0, s5
	ds_read_b128 v[178:181], v153 offset:16384
	ds_read_b128 v[198:201], v153 offset:17408
	ds_read_b128 v[202:205], v153 offset:18432
	ds_read_b128 v[206:209], v153 offset:19456
	ds_read_b128 v[226:229], v153 offset:20480
	ds_read_b128 v[230:233], v153 offset:21504
	ds_read_b128 v[234:237], v153 offset:22528
	ds_read_b128 v[238:241], v153 offset:23552
	global_load_lds_dwordx4 v[150:151], off
	s_add_i32 m0, s5, 0x2000
	s_add_u32 s30, s54, 0x80000
	v_lshl_add_u64 v[210:211], s[54:55], 0, v[130:131]
	s_addc_u32 s31, s55, 0
	s_add_i32 s4, s4, s58
	global_load_lds_dwordx4 v[210:211], off
	v_lshl_add_u64 v[242:243], s[30:31], 0, v[182:183]
	s_mov_b32 m0, s4
	v_lshl_add_u64 v[244:245], s[56:57], 0, v[132:133]
	global_load_lds_dwordx4 v[242:243], off
	v_lshl_add_u64 v[242:243], s[30:31], 0, v[130:131]
	s_add_i32 m0, s4, 0x2000
	s_nop 0
	global_load_lds_dwordx4 v[242:243], off
	v_lshl_add_u64 v[242:243], s[56:57], 0, v[134:135]
	s_mov_b32 m0, s59
	s_nop 0
	global_load_lds_dwordx4 v[242:243], off
	s_mov_b32 m0, s62
	s_nop 0
	global_load_lds_dwordx4 v[244:245], off
	s_waitcnt vmcnt(8)
	s_waitcnt lgkmcnt(0)
	s_setprio 1
	s_barrier
	v_mfma_i32_16x16x64_i8 v[62:65], v[140:143], v[178:181], v[62:65]
	v_mfma_i32_16x16x64_i8 v[54:57], v[154:157], v[178:181], v[54:57]
	v_mfma_i32_16x16x64_i8 v[46:49], v[140:143], v[202:205], v[46:49]
	v_mfma_i32_16x16x64_i8 v[38:41], v[154:157], v[202:205], v[38:41]
	v_mfma_i32_16x16x64_i8 v[30:33], v[140:143], v[226:229], v[30:33]
	v_mfma_i32_16x16x64_i8 v[22:25], v[154:157], v[226:229], v[22:25]
	v_mfma_i32_16x16x64_i8 v[14:17], v[140:143], v[234:237], v[14:17]
	v_mfma_i32_16x16x64_i8 v[6:9], v[154:157], v[234:237], v[6:9]
	v_mfma_i32_16x16x64_i8 v[62:65], v[144:147], v[198:201], v[62:65]
	v_mfma_i32_16x16x64_i8 v[54:57], v[158:161], v[198:201], v[54:57]
	v_mfma_i32_16x16x64_i8 v[46:49], v[144:147], v[206:209], v[46:49]
	v_mfma_i32_16x16x64_i8 v[38:41], v[158:161], v[206:209], v[38:41]
	v_mfma_i32_16x16x64_i8 v[30:33], v[144:147], v[230:233], v[30:33]
	v_mfma_i32_16x16x64_i8 v[22:25], v[158:161], v[230:233], v[22:25]
	v_mfma_i32_16x16x64_i8 v[14:17], v[144:147], v[238:241], v[14:17]
	v_mfma_i32_16x16x64_i8 v[6:9], v[158:161], v[238:241], v[6:9]
	v_mfma_i32_16x16x64_i8 v[58:61], v[162:165], v[178:181], v[58:61]
	v_mfma_i32_16x16x64_i8 v[50:53], v[170:173], v[178:181], v[50:53]
	v_mfma_i32_16x16x64_i8 v[42:45], v[162:165], v[202:205], v[42:45]
	v_mfma_i32_16x16x64_i8 v[34:37], v[170:173], v[202:205], v[34:37]
	v_mfma_i32_16x16x64_i8 v[26:29], v[162:165], v[226:229], v[26:29]
	v_mfma_i32_16x16x64_i8 v[18:21], v[170:173], v[226:229], v[18:21]
	v_mfma_i32_16x16x64_i8 v[10:13], v[162:165], v[234:237], v[10:13]
	v_mfma_i32_16x16x64_i8 v[2:5], v[170:173], v[234:237], v[2:5]
	v_mfma_i32_16x16x64_i8 v[58:61], v[166:169], v[198:201], v[58:61]
	v_mfma_i32_16x16x64_i8 v[50:53], v[174:177], v[198:201], v[50:53]
	v_mfma_i32_16x16x64_i8 v[42:45], v[166:169], v[206:209], v[42:45]
	v_mfma_i32_16x16x64_i8 v[34:37], v[174:177], v[206:209], v[34:37]
	v_mfma_i32_16x16x64_i8 v[26:29], v[166:169], v[230:233], v[26:29]
	v_mfma_i32_16x16x64_i8 v[18:21], v[174:177], v[230:233], v[18:21]
	v_mfma_i32_16x16x64_i8 v[10:13], v[166:169], v[238:241], v[10:13]
	v_mfma_i32_16x16x64_i8 v[2:5], v[174:177], v[238:241], v[2:5]
	s_barrier
; #define PG8_STAGE(bufoff, gbase, voff) do { _Pragma("unroll") for (int _i = 0; _i < 2; ++_i) \
;         __builtin_amdgcn_global_load_lds((const unsigned*)((const char*)(gbase) + (voff)[_i]), (PG8_LAS unsigned*)(lds + (bufoff) + ldsw + _i * 8192), 16, 0, 0); } while (0)
; #define PG8_LDA(dst, b, h) do { _Pragma("unroll") for (int m = 0; m < 4; ++m) _Pragma("unroll") for (int k = 0; k < 2; ++k) dst[m][k] = *(const PG8_LAS bf16x8*)(lds + PG8_SA(b, h) + aoff + m * 2048 + k * 1024); } while (0)
; #define PG8_LDB(dst, b, h) do { _Pragma("unroll") for (int n = 0; n < 2; ++n) _Pragma("unroll") for (int k = 0; k < 2; ++k) dst[n][k] = *(const PG8_LAS bf16x8*)(lds + PG8_SB(b, h) + boff + n * 2048 + k * 1024); } while (0)
; #define PG8_WAIT_V(n) asm volatile("s_waitcnt vmcnt(" #n ")" ::: "memory")
; #define PG8_WAIT_L(n) asm volatile("s_waitcnt lgkmcnt(" #n ")" ::: "memory")
; #define PG8_BAR __builtin_amdgcn_s_barrier()
; #define PG8_SCHED __builtin_amdgcn_sched_barrier(0)
; template <class Epi, class Sched, bool ALIGN_EPI = false, bool SP2 = false, bool I8 = false, bool F16 = false>
; __device__ __forceinline__ void gemm_phase(PG8_LAS unsigned char* lds, const Gemm g, const Sched& S, const Epi& E) {
;     ...
;             PG8_LDB(B0, 1, 0); PG8_LDB(B1, 1, 1); PG8_SCHED; PG8_LDA(At, 1, 0); PG8_STAGE(PG8_SA(0, 1), a2 + hstep, voffA);
;             PG8_WAIT_V(8); PG8_WAIT_L(0); PG8_BAR; PG8_MMA(0, 0, At, B0); PG8_MMA(0, 1, At, B1); PG8_BAR; PG8_SCHED;
;             PG8_LDA(At, 1, 1); PG8_STAGE(PG8_SB(1, 0), b3, voffB); PG8_STAGE(PG8_SB(1, 1), b3 + hstep, voffB); PG8_STAGE(PG8_SA(1, 0), a3, voffA);
;             PG8_WAIT_V(8); PG8_WAIT_L(0); PG8_BAR; PG8_MMA(1, 0, At, B0); PG8_MMA(1, 1, At, B1); PG8_BAR; PG8_SCHED;
;     ...
;         if constexpr (ALIGN_EPI) { if (wr == 0) PG8_BAR; }
	s_setprio 0
	s_add_i32 s4, 0, 0x18000
	v_add_u32_e32 v148, s4, v149
	s_add_i32 s5, 0, 0x1c000
	ds_read_b128 v[140:143], v148
	ds_read_b128 v[144:147], v148 offset:1024
	ds_read_b128 v[154:157], v148 offset:2048
	ds_read_b128 v[158:161], v148 offset:3072
	v_add_u32_e32 v148, s5, v149
	ds_read_b128 v[162:165], v148
	ds_read_b128 v[166:169], v148 offset:1024
	ds_read_b128 v[170:173], v148 offset:2048
	ds_read_b128 v[174:177], v148 offset:3072
	s_add_u32 s30, s56, 0x80000
	s_addc_u32 s31, s57, 0
	s_mov_b32 m0, s64
	v_lshl_add_u64 v[246:247], s[30:31], 0, v[134:135]
	ds_read_b128 v[178:181], v153 offset:32768
	ds_read_b128 v[198:201], v153 offset:33792
	ds_read_b128 v[202:205], v153 offset:34816
	ds_read_b128 v[206:209], v153 offset:35840
	ds_read_b128 v[226:229], v153 offset:36864
	ds_read_b128 v[230:233], v153 offset:37888
	ds_read_b128 v[234:237], v153 offset:38912
	ds_read_b128 v[238:241], v153 offset:39936
	global_load_lds_dwordx4 v[246:247], off
	v_lshl_add_u64 v[246:247], s[30:31], 0, v[132:133]
	s_mov_b32 m0, s65
	s_nop 0
	global_load_lds_dwordx4 v[246:247], off
	s_waitcnt vmcnt(8)
	s_waitcnt lgkmcnt(0)
	s_setprio 1
	s_barrier
	v_mfma_i32_16x16x64_i8 v[126:129], v[140:143], v[178:181], v[126:129]
	v_mfma_i32_16x16x64_i8 v[118:121], v[154:157], v[178:181], v[118:121]
	v_mfma_i32_16x16x64_i8 v[110:113], v[140:143], v[202:205], v[110:113]
	v_mfma_i32_16x16x64_i8 v[102:105], v[154:157], v[202:205], v[102:105]
	v_mfma_i32_16x16x64_i8 v[94:97], v[140:143], v[226:229], v[94:97]
	v_mfma_i32_16x16x64_i8 v[86:89], v[154:157], v[226:229], v[86:89]
	v_mfma_i32_16x16x64_i8 v[78:81], v[140:143], v[234:237], v[78:81]
	v_mfma_i32_16x16x64_i8 v[70:73], v[154:157], v[234:237], v[70:73]
	v_mfma_i32_16x16x64_i8 v[126:129], v[144:147], v[198:201], v[126:129]
	v_mfma_i32_16x16x64_i8 v[118:121], v[158:161], v[198:201], v[118:121]
	v_mfma_i32_16x16x64_i8 v[110:113], v[144:147], v[206:209], v[110:113]
	v_mfma_i32_16x16x64_i8 v[102:105], v[158:161], v[206:209], v[102:105]
	v_mfma_i32_16x16x64_i8 v[94:97], v[144:147], v[230:233], v[94:97]
	v_mfma_i32_16x16x64_i8 v[86:89], v[158:161], v[230:233], v[86:89]
	v_mfma_i32_16x16x64_i8 v[78:81], v[144:147], v[238:241], v[78:81]
	v_mfma_i32_16x16x64_i8 v[70:73], v[158:161], v[238:241], v[70:73]
	v_mfma_i32_16x16x64_i8 v[122:125], v[162:165], v[178:181], v[122:125]
	v_mfma_i32_16x16x64_i8 v[114:117], v[170:173], v[178:181], v[114:117]
	v_mfma_i32_16x16x64_i8 v[106:109], v[162:165], v[202:205], v[106:109]
	v_mfma_i32_16x16x64_i8 v[98:101], v[170:173], v[202:205], v[98:101]
	v_mfma_i32_16x16x64_i8 v[90:93], v[162:165], v[226:229], v[90:93]
	v_mfma_i32_16x16x64_i8 v[82:85], v[170:173], v[226:229], v[82:85]
	v_mfma_i32_16x16x64_i8 v[74:77], v[162:165], v[234:237], v[74:77]
	v_mfma_i32_16x16x64_i8 v[66:69], v[170:173], v[234:237], v[66:69]
	v_mfma_i32_16x16x64_i8 v[122:125], v[166:169], v[198:201], v[122:125]
	v_mfma_i32_16x16x64_i8 v[114:117], v[174:177], v[198:201], v[114:117]
	v_mfma_i32_16x16x64_i8 v[106:109], v[166:169], v[206:209], v[106:109]
	v_mfma_i32_16x16x64_i8 v[98:101], v[174:177], v[206:209], v[98:101]
	v_mfma_i32_16x16x64_i8 v[90:93], v[166:169], v[230:233], v[90:93]
	v_mfma_i32_16x16x64_i8 v[82:85], v[174:177], v[230:233], v[82:85]
	v_mfma_i32_16x16x64_i8 v[74:77], v[166:169], v[238:241], v[74:77]
	v_mfma_i32_16x16x64_i8 v[66:69], v[174:177], v[238:241], v[66:69]
	s_barrier
	s_setprio 0
	s_add_i32 s4, s4, s58
	v_lshl_add_u64 v[150:151], v[150:151], 0, s[74:75]
	s_mov_b32 m0, s4
	ds_read_b128 v[178:181], v153 offset:49152
	ds_read_b128 v[198:201], v153 offset:50176
	ds_read_b128 v[202:205], v153 offset:51200
	ds_read_b128 v[206:209], v153 offset:52224
	ds_read_b128 v[226:229], v153 offset:53248
	ds_read_b128 v[230:233], v153 offset:54272
	ds_read_b128 v[234:237], v153 offset:55296
	ds_read_b128 v[238:241], v153 offset:56320
	global_load_lds_dwordx4 v[150:151], off
	s_add_i32 m0, s4, 0x2000
	s_add_u32 s30, s54, 0x80080
	v_lshl_add_u64 v[150:151], v[210:211], 0, s[74:75]
	s_addc_u32 s31, s55, 0
	s_add_i32 s4, s5, s58
	global_load_lds_dwordx4 v[150:151], off
	v_lshl_add_u64 v[150:151], s[30:31], 0, v[182:183]
	s_mov_b32 m0, s4
	s_nop 0
	global_load_lds_dwordx4 v[150:151], off
	v_lshl_add_u64 v[150:151], s[30:31], 0, v[130:131]
	s_add_i32 m0, s4, 0x2000
	s_nop 0
	global_load_lds_dwordx4 v[150:151], off
	v_lshl_add_u64 v[150:151], v[242:243], 0, s[74:75]
	s_mov_b32 m0, s66
	s_nop 0
	global_load_lds_dwordx4 v[150:151], off
	v_lshl_add_u64 v[150:151], v[244:245], 0, s[74:75]
	s_mov_b32 m0, s67
	s_nop 0
	global_load_lds_dwordx4 v[150:151], off
	s_waitcnt vmcnt(8)
	s_waitcnt lgkmcnt(0)
	s_setprio 1
	s_barrier
	v_mfma_i32_16x16x64_i8 v[62:65], v[140:143], v[178:181], v[62:65]
	v_mfma_i32_16x16x64_i8 v[54:57], v[154:157], v[178:181], v[54:57]
	v_mfma_i32_16x16x64_i8 v[46:49], v[140:143], v[202:205], v[46:49]
	v_mfma_i32_16x16x64_i8 v[38:41], v[154:157], v[202:205], v[38:41]
	v_mfma_i32_16x16x64_i8 v[30:33], v[140:143], v[226:229], v[30:33]
	v_mfma_i32_16x16x64_i8 v[22:25], v[154:157], v[226:229], v[22:25]
	v_mfma_i32_16x16x64_i8 v[14:17], v[140:143], v[234:237], v[14:17]
	v_mfma_i32_16x16x64_i8 v[6:9], v[154:157], v[234:237], v[6:9]
	v_mfma_i32_16x16x64_i8 v[62:65], v[144:147], v[198:201], v[62:65]
	v_mfma_i32_16x16x64_i8 v[54:57], v[158:161], v[198:201], v[54:57]
	v_mfma_i32_16x16x64_i8 v[46:49], v[144:147], v[206:209], v[46:49]
	v_mfma_i32_16x16x64_i8 v[38:41], v[158:161], v[206:209], v[38:41]
	v_mfma_i32_16x16x64_i8 v[30:33], v[144:147], v[230:233], v[30:33]
	v_mfma_i32_16x16x64_i8 v[22:25], v[158:161], v[230:233], v[22:25]
	v_mfma_i32_16x16x64_i8 v[14:17], v[144:147], v[238:241], v[14:17]
	v_mfma_i32_16x16x64_i8 v[6:9], v[158:161], v[238:241], v[6:9]
	v_mfma_i32_16x16x64_i8 v[58:61], v[162:165], v[178:181], v[58:61]
	v_mfma_i32_16x16x64_i8 v[50:53], v[170:173], v[178:181], v[50:53]
	v_mfma_i32_16x16x64_i8 v[42:45], v[162:165], v[202:205], v[42:45]
	v_mfma_i32_16x16x64_i8 v[34:37], v[170:173], v[202:205], v[34:37]
	v_mfma_i32_16x16x64_i8 v[26:29], v[162:165], v[226:229], v[26:29]
	v_mfma_i32_16x16x64_i8 v[18:21], v[170:173], v[226:229], v[18:21]
	v_mfma_i32_16x16x64_i8 v[10:13], v[162:165], v[234:237], v[10:13]
	v_mfma_i32_16x16x64_i8 v[2:5], v[170:173], v[234:237], v[2:5]
	v_mfma_i32_16x16x64_i8 v[58:61], v[166:169], v[198:201], v[58:61]
	v_mfma_i32_16x16x64_i8 v[50:53], v[174:177], v[198:201], v[50:53]
	v_mfma_i32_16x16x64_i8 v[42:45], v[166:169], v[206:209], v[42:45]
	v_mfma_i32_16x16x64_i8 v[34:37], v[174:177], v[206:209], v[34:37]
	v_mfma_i32_16x16x64_i8 v[26:29], v[166:169], v[230:233], v[26:29]
	v_mfma_i32_16x16x64_i8 v[18:21], v[174:177], v[230:233], v[18:21]
	v_mfma_i32_16x16x64_i8 v[10:13], v[166:169], v[238:241], v[10:13]
	v_mfma_i32_16x16x64_i8 v[2:5], v[174:177], v[238:241], v[2:5]
	s_barrier
	s_setprio 0
	s_add_i32 vcc_lo, vcc_lo, 2
	s_add_u32 s52, s52, 0x100
	s_addc_u32 s53, s53, 0
	s_add_u32 s83, s83, 0x100
	s_addc_u32 s85, s85, 0
	s_cmp_gt_u32 vcc_lo, 29
	s_cbranch_scc0 .LBB0_1057
	s_and_b64 vcc, exec, s[36:37]
	s_cbranch_vccz .LBB0_1060
	s_barrier

; #define PG8_STAGE(bufoff, gbase, voff) do { _Pragma("unroll") for (int _i = 0; _i < 2; ++_i) \
;         __builtin_amdgcn_global_load_lds((const unsigned*)((const char*)(gbase) + (voff)[_i]), (PG8_LAS unsigned*)(lds + (bufoff) + ldsw + _i * 8192), 16, 0, 0); } while (0)
; #define PG8_LDA(dst, b, h) do { _Pragma("unroll") for (int m = 0; m < 4; ++m) _Pragma("unroll") for (int k = 0; k < 2; ++k) dst[m][k] = *(const PG8_LAS bf16x8*)(lds + PG8_SA(b, h) + aoff + m * 2048 + k * 1024); } while (0)
; #define PG8_LDB(dst, b, h) do { _Pragma("unroll") for (int n = 0; n < 2; ++n) _Pragma("unroll") for (int k = 0; k < 2; ++k) dst[n][k] = *(const PG8_LAS bf16x8*)(lds + PG8_SB(b, h) + boff + n * 2048 + k * 1024); } while (0)
; #define PG8_WAIT_V(n) asm volatile("s_waitcnt vmcnt(" #n ")" ::: "memory")
; #define PG8_WAIT_L(n) asm volatile("s_waitcnt lgkmcnt(" #n ")" ::: "memory")
; #define PG8_BAR __builtin_amdgcn_s_barrier()
; #define PG8_SCHED __builtin_amdgcn_sched_barrier(0)
; template <class Epi, class Sched, bool ALIGN_EPI = false, bool SP2 = false, bool I8 = false, bool F16 = false>
; __device__ __forceinline__ void gemm_phase(PG8_LAS unsigned char* lds, const Gemm g, const Sched& S, const Epi& E) {
;     ...
;         for (int t = 0; t < nt; t += 2) {
;             const bool last = (t == nt - 2);
;             const char* a1 = cA + (size_t)(t + 1) * kstep;
;             const char* a2 = last ? nA : cA + (size_t)(t + 2) * kstep; const char* b2 = last ? nB : cB + (size_t)(t + 2) * kstep;
;             const char* a3 = a2 + kstep; const char* b3 = b2 + kstep;
;             if (last && has_next) S.a_ready(nxt);
;             if constexpr (SP2) {
;             PG8_LDB(B0, 0, 0); PG8_LDB(B1, 0, 1); PG8_SCHED; PG8_LDA(At, 0, 0); PG8_STAGE(PG8_SA(1, 1), a1 + hstep, voffA);
;             PG8_WAIT_V(8); PG8_WAIT_L(0); PG8_BAR; PG8_MMA(0, 0, At, B0); PG8_MMA(0, 1, At, B1); PG8_BAR; PG8_SCHED;
;     ...
; #pragma unroll
;         for (int a = 0; a < 2; ++a)
; #pragma unroll
;             for (int b = 0; b < 2; ++b)
; #pragma unroll
;                 for (int m = 0; m < 4; ++m)
; #pragma unroll
;                     for (int n = 0; n < 2; ++n) acc[a][b][m][n] = (accv_t){0, 0, 0, 0};
;         cur = nxt; cA = nA; cB = nB; ++ui;
.LBB0_1199:
	s_add_u32 vcc_lo, s54, 0x100
	v_mov_b32_e32 v2, 0
	s_addc_u32 vcc_hi, s55, 0
	s_mov_b32 s30, -2
	v_mov_b32_e32 v3, v2
	v_mov_b32_e32 v4, v2
	v_mov_b32_e32 v5, v2
	v_mov_b32_e32 v6, v2
	v_mov_b32_e32 v7, v2
	v_mov_b32_e32 v8, v2
	v_mov_b32_e32 v9, v2
	v_mov_b32_e32 v18, v2
	v_mov_b32_e32 v19, v2
	v_mov_b32_e32 v20, v2
	v_mov_b32_e32 v21, v2
	v_mov_b32_e32 v22, v2
	v_mov_b32_e32 v23, v2
	v_mov_b32_e32 v24, v2
	v_mov_b32_e32 v25, v2
	v_mov_b32_e32 v34, v2
	v_mov_b32_e32 v35, v2
	v_mov_b32_e32 v36, v2
	v_mov_b32_e32 v37, v2
	v_mov_b32_e32 v38, v2
	v_mov_b32_e32 v39, v2
	v_mov_b32_e32 v40, v2
	v_mov_b32_e32 v41, v2
	v_mov_b32_e32 v50, v2
	v_mov_b32_e32 v51, v2
	v_mov_b32_e32 v52, v2
	v_mov_b32_e32 v53, v2
	v_mov_b32_e32 v54, v2
	v_mov_b32_e32 v55, v2
	v_mov_b32_e32 v56, v2
	v_mov_b32_e32 v57, v2
	v_mov_b32_e32 v10, v2
	v_mov_b32_e32 v11, v2
	v_mov_b32_e32 v12, v2
	v_mov_b32_e32 v13, v2
	v_mov_b32_e32 v14, v2
	v_mov_b32_e32 v15, v2
	v_mov_b32_e32 v16, v2
	v_mov_b32_e32 v17, v2
	v_mov_b32_e32 v26, v2
	v_mov_b32_e32 v27, v2
	v_mov_b32_e32 v28, v2
	v_mov_b32_e32 v29, v2
	v_mov_b32_e32 v30, v2
	v_mov_b32_e32 v31, v2
	v_mov_b32_e32 v32, v2
	v_mov_b32_e32 v33, v2
	v_mov_b32_e32 v42, v2
	v_mov_b32_e32 v43, v2
	v_mov_b32_e32 v44, v2
	v_mov_b32_e32 v45, v2
	v_mov_b32_e32 v46, v2
	v_mov_b32_e32 v47, v2
	v_mov_b32_e32 v48, v2
	v_mov_b32_e32 v49, v2
	v_mov_b32_e32 v58, v2
	v_mov_b32_e32 v59, v2
	v_mov_b32_e32 v60, v2
	v_mov_b32_e32 v61, v2
	v_mov_b32_e32 v62, v2
	v_mov_b32_e32 v63, v2
	v_mov_b32_e32 v64, v2
	v_mov_b32_e32 v65, v2
	v_mov_b32_e32 v66, v2
	v_mov_b32_e32 v67, v2
	v_mov_b32_e32 v68, v2
	v_mov_b32_e32 v69, v2
	v_mov_b32_e32 v70, v2
	v_mov_b32_e32 v71, v2
	v_mov_b32_e32 v72, v2
	v_mov_b32_e32 v73, v2
	v_mov_b32_e32 v82, v2
	v_mov_b32_e32 v83, v2
	v_mov_b32_e32 v84, v2
	v_mov_b32_e32 v85, v2
	v_mov_b32_e32 v86, v2
	v_mov_b32_e32 v87, v2
	v_mov_b32_e32 v88, v2
	v_mov_b32_e32 v89, v2
	v_mov_b32_e32 v98, v2
	v_mov_b32_e32 v99, v2
	v_mov_b32_e32 v100, v2
	v_mov_b32_e32 v101, v2
	v_mov_b32_e32 v102, v2
	v_mov_b32_e32 v103, v2
	v_mov_b32_e32 v104, v2
	v_mov_b32_e32 v105, v2
	v_mov_b32_e32 v114, v2
	v_mov_b32_e32 v115, v2
	v_mov_b32_e32 v116, v2
	v_mov_b32_e32 v117, v2
	v_mov_b32_e32 v118, v2
	v_mov_b32_e32 v119, v2
	v_mov_b32_e32 v120, v2
	v_mov_b32_e32 v121, v2
	v_mov_b32_e32 v74, v2
	v_mov_b32_e32 v75, v2
	v_mov_b32_e32 v76, v2
	v_mov_b32_e32 v77, v2
	v_mov_b32_e32 v78, v2
	v_mov_b32_e32 v79, v2
	v_mov_b32_e32 v80, v2
	v_mov_b32_e32 v81, v2
	v_mov_b32_e32 v90, v2
	v_mov_b32_e32 v91, v2
	v_mov_b32_e32 v92, v2
	v_mov_b32_e32 v93, v2
	v_mov_b32_e32 v94, v2
	v_mov_b32_e32 v95, v2
	v_mov_b32_e32 v96, v2
	v_mov_b32_e32 v97, v2
	v_mov_b32_e32 v106, v2
	v_mov_b32_e32 v107, v2
	v_mov_b32_e32 v108, v2
	v_mov_b32_e32 v109, v2
	v_mov_b32_e32 v110, v2
	v_mov_b32_e32 v111, v2
	v_mov_b32_e32 v112, v2
	v_mov_b32_e32 v113, v2
	v_mov_b32_e32 v122, v2
	v_mov_b32_e32 v123, v2
	v_mov_b32_e32 v124, v2
	v_mov_b32_e32 v125, v2
	v_mov_b32_e32 v126, v2
	v_mov_b32_e32 v127, v2
	v_mov_b32_e32 v128, v2
	v_mov_b32_e32 v129, v2
.LBB0_1200:
	s_add_u32 s54, s52, 0x100
	s_addc_u32 s55, s53, 0
	s_add_i32 s31, 0, 0x10000
	s_cmpk_eq_i32 s30, 0x52
	s_cselect_b32 s59, s7, s55
	s_cselect_b32 s58, s6, s54
	s_cselect_b32 s57, s51, vcc_hi
	s_cselect_b32 s56, s50, vcc_lo
	s_add_i32 s34, 0, 0x14000
	v_add_u32_e32 v152, s31, v156
	v_add_u32_e32 v159, s34, v156
	ds_read_b128 v[140:143], v152
	ds_read_b128 v[144:147], v152 offset:1024
	ds_read_b128 v[148:151], v152 offset:2048
	ds_read_b128 v[152:155], v152 offset:3072
	ds_read_b128 v[160:163], v159
	ds_read_b128 v[164:167], v159 offset:1024
	ds_read_b128 v[168:171], v159 offset:2048
	ds_read_b128 v[172:175], v159 offset:3072
	v_lshl_add_u64 v[180:181], s[52:53], 0, v[136:137]
	s_add_i32 m0, s64, 0xc000
	ds_read_b128 v[176:179], v158
	ds_read_b128 v[198:201], v158 offset:1024
	ds_read_b128 v[202:205], v158 offset:2048
	ds_read_b128 v[206:209], v158 offset:3072
	ds_read_b128 v[226:229], v158 offset:4096
	ds_read_b128 v[230:233], v158 offset:5120
	ds_read_b128 v[234:237], v158 offset:6144
	ds_read_b128 v[238:241], v158 offset:7168
	global_load_lds_dwordx4 v[180:181], off
	v_lshl_add_u64 v[180:181], s[52:53], 0, v[138:139]
	s_add_i32 m0, s64, 0xe000
	s_nop 0
	global_load_lds_dwordx4 v[180:181], off
	s_waitcnt vmcnt(8)
	s_waitcnt lgkmcnt(0)
	s_setprio 1
	s_barrier
	v_mfma_i32_16x16x64_i8 v[126:129], v[140:143], v[176:179], v[126:129]
	v_mfma_i32_16x16x64_i8 v[122:125], v[148:151], v[176:179], v[122:125]
	v_mfma_i32_16x16x64_i8 v[110:113], v[140:143], v[202:205], v[110:113]
	v_mfma_i32_16x16x64_i8 v[106:109], v[148:151], v[202:205], v[106:109]
	v_mfma_i32_16x16x64_i8 v[94:97], v[140:143], v[226:229], v[94:97]
	v_mfma_i32_16x16x64_i8 v[90:93], v[148:151], v[226:229], v[90:93]
	v_mfma_i32_16x16x64_i8 v[78:81], v[140:143], v[234:237], v[78:81]
	v_mfma_i32_16x16x64_i8 v[74:77], v[148:151], v[234:237], v[74:77]
	v_mfma_i32_16x16x64_i8 v[126:129], v[144:147], v[198:201], v[126:129]
	v_mfma_i32_16x16x64_i8 v[122:125], v[152:155], v[198:201], v[122:125]
	v_mfma_i32_16x16x64_i8 v[110:113], v[144:147], v[206:209], v[110:113]
	v_mfma_i32_16x16x64_i8 v[106:109], v[152:155], v[206:209], v[106:109]
	v_mfma_i32_16x16x64_i8 v[94:97], v[144:147], v[230:233], v[94:97]
	v_mfma_i32_16x16x64_i8 v[90:93], v[152:155], v[230:233], v[90:93]
	v_mfma_i32_16x16x64_i8 v[78:81], v[144:147], v[238:241], v[78:81]
	v_mfma_i32_16x16x64_i8 v[74:77], v[152:155], v[238:241], v[74:77]
	v_mfma_i32_16x16x64_i8 v[118:121], v[160:163], v[176:179], v[118:121]
	v_mfma_i32_16x16x64_i8 v[114:117], v[168:171], v[176:179], v[114:117]
	v_mfma_i32_16x16x64_i8 v[102:105], v[160:163], v[202:205], v[102:105]
	v_mfma_i32_16x16x64_i8 v[98:101], v[168:171], v[202:205], v[98:101]
	v_mfma_i32_16x16x64_i8 v[86:89], v[160:163], v[226:229], v[86:89]
	v_mfma_i32_16x16x64_i8 v[82:85], v[168:171], v[226:229], v[82:85]
	v_mfma_i32_16x16x64_i8 v[70:73], v[160:163], v[234:237], v[70:73]
	v_mfma_i32_16x16x64_i8 v[66:69], v[168:171], v[234:237], v[66:69]
	v_mfma_i32_16x16x64_i8 v[118:121], v[164:167], v[198:201], v[118:121]
	v_mfma_i32_16x16x64_i8 v[114:117], v[172:175], v[198:201], v[114:117]
	v_mfma_i32_16x16x64_i8 v[102:105], v[164:167], v[206:209], v[102:105]
	v_mfma_i32_16x16x64_i8 v[98:101], v[172:175], v[206:209], v[98:101]
	v_mfma_i32_16x16x64_i8 v[86:89], v[164:167], v[230:233], v[86:89]
	v_mfma_i32_16x16x64_i8 v[82:85], v[172:175], v[230:233], v[82:85]
	v_mfma_i32_16x16x64_i8 v[70:73], v[164:167], v[238:241], v[70:73]
	v_mfma_i32_16x16x64_i8 v[66:69], v[172:175], v[238:241], v[66:69]
	s_barrier
; #define PG8_STAGE(bufoff, gbase, voff) do { _Pragma("unroll") for (int _i = 0; _i < 2; ++_i) \
;         __builtin_amdgcn_global_load_lds((const unsigned*)((const char*)(gbase) + (voff)[_i]), (PG8_LAS unsigned*)(lds + (bufoff) + ldsw + _i * 8192), 16, 0, 0); } while (0)
; #define PG8_LDA(dst, b, h) do { _Pragma("unroll") for (int m = 0; m < 4; ++m) _Pragma("unroll") for (int k = 0; k < 2; ++k) dst[m][k] = *(const PG8_LAS bf16x8*)(lds + PG8_SA(b, h) + aoff + m * 2048 + k * 1024); } while (0)
; #define PG8_LDB(dst, b, h) do { _Pragma("unroll") for (int n = 0; n < 2; ++n) _Pragma("unroll") for (int k = 0; k < 2; ++k) dst[n][k] = *(const PG8_LAS bf16x8*)(lds + PG8_SB(b, h) + boff + n * 2048 + k * 1024); } while (0)
; #define PG8_WAIT_V(n) asm volatile("s_waitcnt vmcnt(" #n ")" ::: "memory")
; #define PG8_WAIT_L(n) asm volatile("s_waitcnt lgkmcnt(" #n ")" ::: "memory")
; #define PG8_BAR __builtin_amdgcn_s_barrier()
; #define PG8_SCHED __builtin_amdgcn_sched_barrier(0)
; template <class Epi, class Sched, bool ALIGN_EPI = false, bool SP2 = false, bool I8 = false, bool F16 = false>
; __device__ __forceinline__ void gemm_phase(PG8_LAS unsigned char* lds, const Gemm g, const Sched& S, const Epi& E) {
;     ...
;             PG8_LDA(At, 0, 1); PG8_STAGE(PG8_SB(0, 0), b2, voffB); PG8_STAGE(PG8_SB(0, 1), b2 + hstep, voffB); PG8_STAGE(PG8_SA(0, 0), a2, voffA);
;             PG8_WAIT_V(8); PG8_WAIT_L(0); PG8_BAR; PG8_MMA(1, 0, At, B0); PG8_MMA(1, 1, At, B1); PG8_BAR; PG8_SCHED;
;             PG8_LDB(B0, 1, 0); PG8_LDB(B1, 1, 1); PG8_SCHED; PG8_LDA(At, 1, 0); PG8_STAGE(PG8_SA(0, 1), a2 + hstep, voffA);
;             PG8_WAIT_V(8); PG8_WAIT_L(0); PG8_BAR; PG8_MMA(0, 0, At, B0); PG8_MMA(0, 1, At, B1); PG8_BAR; PG8_SCHED;
	s_setprio 0
	s_add_i32 s31, s31, s62
	v_lshl_add_u64 v[180:181], s[56:57], 0, v[182:183]
	s_mov_b32 m0, s31
	ds_read_b128 v[176:179], v158 offset:16384
	ds_read_b128 v[198:201], v158 offset:17408
	ds_read_b128 v[202:205], v158 offset:18432
	ds_read_b128 v[206:209], v158 offset:19456
	ds_read_b128 v[226:229], v158 offset:20480
	ds_read_b128 v[230:233], v158 offset:21504
	ds_read_b128 v[234:237], v158 offset:22528
	ds_read_b128 v[238:241], v158 offset:23552
	global_load_lds_dwordx4 v[180:181], off
	s_add_i32 m0, s31, 0x2000
	s_add_u32 s52, s56, 0x158000
	v_lshl_add_u64 v[210:211], s[56:57], 0, v[130:131]
	s_addc_u32 s53, s57, 0
	s_add_i32 s31, s34, s62
	global_load_lds_dwordx4 v[210:211], off
	v_lshl_add_u64 v[242:243], s[52:53], 0, v[182:183]
	s_mov_b32 m0, s31
	v_lshl_add_u64 v[244:245], s[58:59], 0, v[132:133]
	global_load_lds_dwordx4 v[242:243], off
	v_lshl_add_u64 v[242:243], s[52:53], 0, v[130:131]
	s_add_i32 m0, s31, 0x2000
	s_nop 0
	global_load_lds_dwordx4 v[242:243], off
	v_lshl_add_u64 v[242:243], s[58:59], 0, v[134:135]
	s_mov_b32 m0, s64
	s_nop 0
	global_load_lds_dwordx4 v[242:243], off
	s_mov_b32 m0, s65
	s_nop 0
	global_load_lds_dwordx4 v[244:245], off
	s_waitcnt vmcnt(8)
	s_waitcnt lgkmcnt(0)
	s_setprio 1
	s_barrier
	v_mfma_i32_16x16x64_i8 v[62:65], v[140:143], v[176:179], v[62:65]
	v_mfma_i32_16x16x64_i8 v[58:61], v[148:151], v[176:179], v[58:61]
	v_mfma_i32_16x16x64_i8 v[46:49], v[140:143], v[202:205], v[46:49]
	v_mfma_i32_16x16x64_i8 v[42:45], v[148:151], v[202:205], v[42:45]
	v_mfma_i32_16x16x64_i8 v[30:33], v[140:143], v[226:229], v[30:33]
	v_mfma_i32_16x16x64_i8 v[26:29], v[148:151], v[226:229], v[26:29]
	v_mfma_i32_16x16x64_i8 v[14:17], v[140:143], v[234:237], v[14:17]
	v_mfma_i32_16x16x64_i8 v[10:13], v[148:151], v[234:237], v[10:13]
	v_mfma_i32_16x16x64_i8 v[62:65], v[144:147], v[198:201], v[62:65]
	v_mfma_i32_16x16x64_i8 v[58:61], v[152:155], v[198:201], v[58:61]
	v_mfma_i32_16x16x64_i8 v[46:49], v[144:147], v[206:209], v[46:49]
	v_mfma_i32_16x16x64_i8 v[42:45], v[152:155], v[206:209], v[42:45]
	v_mfma_i32_16x16x64_i8 v[30:33], v[144:147], v[230:233], v[30:33]
	v_mfma_i32_16x16x64_i8 v[26:29], v[152:155], v[230:233], v[26:29]
	v_mfma_i32_16x16x64_i8 v[14:17], v[144:147], v[238:241], v[14:17]
	v_mfma_i32_16x16x64_i8 v[10:13], v[152:155], v[238:241], v[10:13]
	v_mfma_i32_16x16x64_i8 v[54:57], v[160:163], v[176:179], v[54:57]
	v_mfma_i32_16x16x64_i8 v[50:53], v[168:171], v[176:179], v[50:53]
	v_mfma_i32_16x16x64_i8 v[38:41], v[160:163], v[202:205], v[38:41]
	v_mfma_i32_16x16x64_i8 v[34:37], v[168:171], v[202:205], v[34:37]
	v_mfma_i32_16x16x64_i8 v[22:25], v[160:163], v[226:229], v[22:25]
	v_mfma_i32_16x16x64_i8 v[18:21], v[168:171], v[226:229], v[18:21]
	v_mfma_i32_16x16x64_i8 v[6:9], v[160:163], v[234:237], v[6:9]
	v_mfma_i32_16x16x64_i8 v[2:5], v[168:171], v[234:237], v[2:5]
	v_mfma_i32_16x16x64_i8 v[54:57], v[164:167], v[198:201], v[54:57]
	v_mfma_i32_16x16x64_i8 v[50:53], v[172:175], v[198:201], v[50:53]
	v_mfma_i32_16x16x64_i8 v[38:41], v[164:167], v[206:209], v[38:41]
	v_mfma_i32_16x16x64_i8 v[34:37], v[172:175], v[206:209], v[34:37]
	v_mfma_i32_16x16x64_i8 v[22:25], v[164:167], v[230:233], v[22:25]
	v_mfma_i32_16x16x64_i8 v[18:21], v[172:175], v[230:233], v[18:21]
	v_mfma_i32_16x16x64_i8 v[6:9], v[164:167], v[238:241], v[6:9]
	v_mfma_i32_16x16x64_i8 v[2:5], v[172:175], v[238:241], v[2:5]
	s_barrier
	s_setprio 0
	s_add_i32 s31, 0, 0x18000
	s_add_i32 s34, 0, 0x1c000
	v_add_u32_e32 v152, s31, v156
	v_add_u32_e32 v159, s34, v156
	ds_read_b128 v[140:143], v152
	ds_read_b128 v[144:147], v152 offset:1024
	ds_read_b128 v[148:151], v152 offset:2048
	ds_read_b128 v[152:155], v152 offset:3072
	ds_read_b128 v[160:163], v159
	ds_read_b128 v[164:167], v159 offset:1024
	ds_read_b128 v[168:171], v159 offset:2048
	ds_read_b128 v[172:175], v159 offset:3072
	s_add_u32 s52, s58, 0x158000
	s_addc_u32 s53, s59, 0
	s_mov_b32 m0, s66
	v_lshl_add_u64 v[246:247], s[52:53], 0, v[134:135]
	ds_read_b128 v[176:179], v158 offset:32768
	ds_read_b128 v[198:201], v158 offset:33792
	ds_read_b128 v[202:205], v158 offset:34816
	ds_read_b128 v[206:209], v158 offset:35840
	ds_read_b128 v[226:229], v158 offset:36864
	ds_read_b128 v[230:233], v158 offset:37888
	ds_read_b128 v[234:237], v158 offset:38912
	ds_read_b128 v[238:241], v158 offset:39936
	global_load_lds_dwordx4 v[246:247], off
	v_lshl_add_u64 v[246:247], s[52:53], 0, v[132:133]
	s_mov_b32 m0, s67
	s_nop 0
	global_load_lds_dwordx4 v[246:247], off
	s_waitcnt vmcnt(8)
	s_waitcnt lgkmcnt(0)
	s_setprio 1
	s_barrier
; #define PG8_STAGE(bufoff, gbase, voff) do { _Pragma("unroll") for (int _i = 0; _i < 2; ++_i) \
;         __builtin_amdgcn_global_load_lds((const unsigned*)((const char*)(gbase) + (voff)[_i]), (PG8_LAS unsigned*)(lds + (bufoff) + ldsw + _i * 8192), 16, 0, 0); } while (0)
; #define PG8_LDA(dst, b, h) do { _Pragma("unroll") for (int m = 0; m < 4; ++m) _Pragma("unroll") for (int k = 0; k < 2; ++k) dst[m][k] = *(const PG8_LAS bf16x8*)(lds + PG8_SA(b, h) + aoff + m * 2048 + k * 1024); } while (0)
; #define PG8_WAIT_V(n) asm volatile("s_waitcnt vmcnt(" #n ")" ::: "memory")
; #define PG8_WAIT_L(n) asm volatile("s_waitcnt lgkmcnt(" #n ")" ::: "memory")
; #define PG8_BAR __builtin_amdgcn_s_barrier()
; #define PG8_SCHED __builtin_amdgcn_sched_barrier(0)
; template <class Epi, class Sched, bool ALIGN_EPI = false, bool SP2 = false, bool I8 = false, bool F16 = false>
; __device__ __forceinline__ void gemm_phase(PG8_LAS unsigned char* lds, const Gemm g, const Sched& S, const Epi& E) {
;     ...
;             PG8_WAIT_V(8); PG8_WAIT_L(0); PG8_BAR; PG8_MMA(0, 0, At, B0); PG8_MMA(0, 1, At, B1); PG8_BAR; PG8_SCHED;
;             PG8_LDA(At, 1, 1); PG8_STAGE(PG8_SB(1, 0), b3, voffB); PG8_STAGE(PG8_SB(1, 1), b3 + hstep, voffB); PG8_STAGE(PG8_SA(1, 0), a3, voffA);
;             PG8_WAIT_V(8); PG8_WAIT_L(0); PG8_BAR; PG8_MMA(1, 0, At, B0); PG8_MMA(1, 1, At, B1); PG8_BAR; PG8_SCHED;
;     ...
;         if constexpr (ALIGN_EPI) { if (wr == 0) PG8_BAR; }
	v_mfma_i32_16x16x64_i8 v[126:129], v[140:143], v[176:179], v[126:129]
	v_mfma_i32_16x16x64_i8 v[122:125], v[148:151], v[176:179], v[122:125]
	v_mfma_i32_16x16x64_i8 v[110:113], v[140:143], v[202:205], v[110:113]
	v_mfma_i32_16x16x64_i8 v[106:109], v[148:151], v[202:205], v[106:109]
	v_mfma_i32_16x16x64_i8 v[94:97], v[140:143], v[226:229], v[94:97]
	v_mfma_i32_16x16x64_i8 v[90:93], v[148:151], v[226:229], v[90:93]
	v_mfma_i32_16x16x64_i8 v[78:81], v[140:143], v[234:237], v[78:81]
	v_mfma_i32_16x16x64_i8 v[74:77], v[148:151], v[234:237], v[74:77]
	v_mfma_i32_16x16x64_i8 v[126:129], v[144:147], v[198:201], v[126:129]
	v_mfma_i32_16x16x64_i8 v[122:125], v[152:155], v[198:201], v[122:125]
	v_mfma_i32_16x16x64_i8 v[110:113], v[144:147], v[206:209], v[110:113]
	v_mfma_i32_16x16x64_i8 v[106:109], v[152:155], v[206:209], v[106:109]
	v_mfma_i32_16x16x64_i8 v[94:97], v[144:147], v[230:233], v[94:97]
	v_mfma_i32_16x16x64_i8 v[90:93], v[152:155], v[230:233], v[90:93]
	v_mfma_i32_16x16x64_i8 v[78:81], v[144:147], v[238:241], v[78:81]
	v_mfma_i32_16x16x64_i8 v[74:77], v[152:155], v[238:241], v[74:77]
	v_mfma_i32_16x16x64_i8 v[118:121], v[160:163], v[176:179], v[118:121]
	v_mfma_i32_16x16x64_i8 v[114:117], v[168:171], v[176:179], v[114:117]
	v_mfma_i32_16x16x64_i8 v[102:105], v[160:163], v[202:205], v[102:105]
	v_mfma_i32_16x16x64_i8 v[98:101], v[168:171], v[202:205], v[98:101]
	v_mfma_i32_16x16x64_i8 v[86:89], v[160:163], v[226:229], v[86:89]
	v_mfma_i32_16x16x64_i8 v[82:85], v[168:171], v[226:229], v[82:85]
	v_mfma_i32_16x16x64_i8 v[70:73], v[160:163], v[234:237], v[70:73]
	v_mfma_i32_16x16x64_i8 v[66:69], v[168:171], v[234:237], v[66:69]
	v_mfma_i32_16x16x64_i8 v[118:121], v[164:167], v[198:201], v[118:121]
	v_mfma_i32_16x16x64_i8 v[114:117], v[172:175], v[198:201], v[114:117]
	v_mfma_i32_16x16x64_i8 v[102:105], v[164:167], v[206:209], v[102:105]
	v_mfma_i32_16x16x64_i8 v[98:101], v[172:175], v[206:209], v[98:101]
	v_mfma_i32_16x16x64_i8 v[86:89], v[164:167], v[230:233], v[86:89]
	v_mfma_i32_16x16x64_i8 v[82:85], v[172:175], v[230:233], v[82:85]
	v_mfma_i32_16x16x64_i8 v[70:73], v[164:167], v[238:241], v[70:73]
	v_mfma_i32_16x16x64_i8 v[66:69], v[172:175], v[238:241], v[66:69]
	s_barrier
	s_setprio 0
	s_add_i32 s31, s31, s62
	v_lshl_add_u64 v[180:181], v[180:181], 0, s[74:75]
	s_mov_b32 m0, s31
	ds_read_b128 v[176:179], v158 offset:49152
	ds_read_b128 v[198:201], v158 offset:50176
	ds_read_b128 v[202:205], v158 offset:51200
	ds_read_b128 v[206:209], v158 offset:52224
	ds_read_b128 v[226:229], v158 offset:53248
	ds_read_b128 v[230:233], v158 offset:54272
	ds_read_b128 v[234:237], v158 offset:55296
	ds_read_b128 v[238:241], v158 offset:56320
	global_load_lds_dwordx4 v[180:181], off
	s_add_i32 m0, s31, 0x2000
	s_add_u32 s52, s56, 0x158080
	v_lshl_add_u64 v[180:181], v[210:211], 0, s[74:75]
	s_addc_u32 s53, s57, 0
	s_add_i32 s31, s34, s62
	global_load_lds_dwordx4 v[180:181], off
	v_lshl_add_u64 v[180:181], s[52:53], 0, v[182:183]
	s_mov_b32 m0, s31
	s_nop 0
	global_load_lds_dwordx4 v[180:181], off
	v_lshl_add_u64 v[180:181], s[52:53], 0, v[130:131]
	s_add_i32 m0, s31, 0x2000
	s_nop 0
	global_load_lds_dwordx4 v[180:181], off
	v_lshl_add_u64 v[180:181], v[242:243], 0, s[74:75]
	s_mov_b32 m0, s68
	s_nop 0
	global_load_lds_dwordx4 v[180:181], off
	v_lshl_add_u64 v[180:181], v[244:245], 0, s[74:75]
	s_mov_b32 m0, s69
	s_nop 0
	global_load_lds_dwordx4 v[180:181], off
	s_waitcnt vmcnt(8)
	s_waitcnt lgkmcnt(0)
	s_setprio 1
	s_barrier
	v_mfma_i32_16x16x64_i8 v[62:65], v[140:143], v[176:179], v[62:65]
	v_mfma_i32_16x16x64_i8 v[58:61], v[148:151], v[176:179], v[58:61]
	v_mfma_i32_16x16x64_i8 v[46:49], v[140:143], v[202:205], v[46:49]
	v_mfma_i32_16x16x64_i8 v[42:45], v[148:151], v[202:205], v[42:45]
	v_mfma_i32_16x16x64_i8 v[30:33], v[140:143], v[226:229], v[30:33]
	v_mfma_i32_16x16x64_i8 v[26:29], v[148:151], v[226:229], v[26:29]
	v_mfma_i32_16x16x64_i8 v[14:17], v[140:143], v[234:237], v[14:17]
	v_mfma_i32_16x16x64_i8 v[10:13], v[148:151], v[234:237], v[10:13]
	v_mfma_i32_16x16x64_i8 v[62:65], v[144:147], v[198:201], v[62:65]
	v_mfma_i32_16x16x64_i8 v[58:61], v[152:155], v[198:201], v[58:61]
	v_mfma_i32_16x16x64_i8 v[46:49], v[144:147], v[206:209], v[46:49]
	v_mfma_i32_16x16x64_i8 v[42:45], v[152:155], v[206:209], v[42:45]
	v_mfma_i32_16x16x64_i8 v[30:33], v[144:147], v[230:233], v[30:33]
	v_mfma_i32_16x16x64_i8 v[26:29], v[152:155], v[230:233], v[26:29]
	v_mfma_i32_16x16x64_i8 v[14:17], v[144:147], v[238:241], v[14:17]
	v_mfma_i32_16x16x64_i8 v[10:13], v[152:155], v[238:241], v[10:13]
	v_mfma_i32_16x16x64_i8 v[54:57], v[160:163], v[176:179], v[54:57]
	v_mfma_i32_16x16x64_i8 v[50:53], v[168:171], v[176:179], v[50:53]
	v_mfma_i32_16x16x64_i8 v[38:41], v[160:163], v[202:205], v[38:41]
	v_mfma_i32_16x16x64_i8 v[34:37], v[168:171], v[202:205], v[34:37]
	v_mfma_i32_16x16x64_i8 v[22:25], v[160:163], v[226:229], v[22:25]
	v_mfma_i32_16x16x64_i8 v[18:21], v[168:171], v[226:229], v[18:21]
	v_mfma_i32_16x16x64_i8 v[6:9], v[160:163], v[234:237], v[6:9]
	v_mfma_i32_16x16x64_i8 v[2:5], v[168:171], v[234:237], v[2:5]
	v_mfma_i32_16x16x64_i8 v[54:57], v[164:167], v[198:201], v[54:57]
	v_mfma_i32_16x16x64_i8 v[50:53], v[172:175], v[198:201], v[50:53]
	v_mfma_i32_16x16x64_i8 v[38:41], v[164:167], v[206:209], v[38:41]
	v_mfma_i32_16x16x64_i8 v[34:37], v[172:175], v[206:209], v[34:37]
	v_mfma_i32_16x16x64_i8 v[22:25], v[164:167], v[230:233], v[22:25]
	v_mfma_i32_16x16x64_i8 v[18:21], v[172:175], v[230:233], v[18:21]
	v_mfma_i32_16x16x64_i8 v[6:9], v[164:167], v[238:241], v[6:9]
	v_mfma_i32_16x16x64_i8 v[2:5], v[172:175], v[238:241], v[2:5]
	s_barrier
	s_setprio 0
	s_add_i32 s30, s30, 2
	s_add_u32 vcc_lo, vcc_lo, 0x100
	s_addc_u32 vcc_hi, vcc_hi, 0
	s_cmpk_gt_u32 s30, 0x53
	s_mov_b64 s[52:53], s[54:55]
	s_cbranch_scc0 .LBB0_1200
	s_and_b64 vcc, exec, s[46:47]
	s_cbranch_vccz .LBB0_1203
	s_barrier
